# prep_item weight-slab staging: 12+8 serialized global load/wait/LDS-write round trips replaced by batched loads with a counted vmcnt ladder
# baseline (speedup 1.0000x reference)
; DI int opaque_tid() { int t = threadIdx.x; asm volatile("" : "+v"(t)); return t; }
; DI void prep_item(const Params& p, int layer, int item, char* smem) {
;     ...
;   const int tid = opaque_tid(), lane = tid & 63, wave = __builtin_amdgcn_readfirstlane(tid >> 6), r = lane & 31, h = lane >> 5;
;   const int tg = (item >> 3) * 4 + wave, hd = item & 7;
;   const int token = tg * 32 + r, b = token >> 12, s = token & 4095;
;   u16 (*sWq)[264] = (u16 (*)[264])smem;
;   u16 (*sWk)[136] = (u16 (*)[136])smem;
;   {
;     const u16* src = WUQ + (size_t)(hd * 96) * 256;
; #pragma unroll
;     for (int i = 0; i < 12; ++i) {
;       const int idx = tid + 256 * i, row = idx >> 5, c = idx & 31;
;       *(uint4*)&sWq[row][c * 8] = *(const uint4*)(src + (size_t)row * 256 + c * 8);
;     }
;   }
;   __syncthreads();
.LBB0_348:
	s_and_b64 vcc, exec, s[0:1]
	s_cbranch_vccz .LBB0_357
	v_mov_b32_e32 v159, v128
	s_lshr_b32 s1, s59, 1
	v_readfirstlane_b32 s0, v159
	s_ashr_i32 s0, s0, 6
	s_and_b32 s1, s1, 0x1fc
	s_add_i32 s0, s0, s1
	s_and_b32 s1, s59, 7
	s_lshl_b32 s5, s0, 5
	s_mul_i32 s12, s1, 0xc000
	v_readlane_b32 s13, v255, 1
	s_add_u32 s12, s13, s12
	v_readlane_b32 s13, v255, 2
	v_lshlrev_b32_e32 v162, 4, v159
	v_ashrrev_i32_e32 v4, 5, v159
	s_addc_u32 s13, s13, 0
	v_and_b32_e32 v2, 0x1f0, v162
	s_waitcnt lgkmcnt(0)
	v_ashrrev_i32_e32 v5, 31, v4
	v_lshl_add_u64 v[8:9], s[12:13], 0, v[2:3]
	v_lshlrev_b64 v[6:7], 9, v[4:5]
	v_lshl_add_u64 v[6:7], v[8:9], 0, v[6:7]
	s_movk_i32 s14, 0x210
	v_mad_u64_u32 v[10:11], s[12:13], v4, s14, v[2:3]
	global_load_dwordx4 v[16:19], v[6:7], off
	v_add_u32_e32 v163, 0x100, v159
	v_add_u32_e32 v164, 0x200, v159
	v_add_u32_e32 v165, 0x300, v159
	v_add_u32_e32 v166, 0x400, v159
	v_add_u32_e32 v167, 0x500, v159
	v_add_u32_e32 v168, 0x600, v159
	v_add_u32_e32 v169, 0x700, v159
	v_add_u32_e32 v1, 0x800, v159
	v_and_b32_e32 v161, 31, v159
	v_or_b32_e32 v0, s5, v161
	v_and_b32_e32 v158, 63, v159
	v_cmp_gt_u32_e32 vcc, 32, v158
	v_bfe_u32 v170, v159, 5, 1
	v_lshlrev_b32_e32 v154, 4, v170
	v_mov_b32_e32 v155, v3
	s_mov_b32 s30, 0x800000
	v_mad_u32_u24 v173, v161, s14, v154
	v_ashrrev_i32_e32 v4, 5, v163
	v_ashrrev_i32_e32 v5, 31, v4
	v_lshlrev_b64 v[6:7], 9, v[4:5]
	v_lshl_add_u64 v[6:7], v[8:9], 0, v[6:7]
	global_load_dwordx4 v[20:23], v[6:7], off
	v_ashrrev_i32_e32 v4, 5, v164
	v_ashrrev_i32_e32 v5, 31, v4
	v_lshlrev_b64 v[6:7], 9, v[4:5]
	v_lshl_add_u64 v[6:7], v[8:9], 0, v[6:7]
	global_load_dwordx4 v[24:27], v[6:7], off
	v_ashrrev_i32_e32 v4, 5, v165
	v_ashrrev_i32_e32 v5, 31, v4
	v_lshlrev_b64 v[6:7], 9, v[4:5]
	v_lshl_add_u64 v[6:7], v[8:9], 0, v[6:7]
	global_load_dwordx4 v[28:31], v[6:7], off
	v_ashrrev_i32_e32 v4, 5, v166
	v_ashrrev_i32_e32 v5, 31, v4
	v_lshlrev_b64 v[6:7], 9, v[4:5]
	v_lshl_add_u64 v[6:7], v[8:9], 0, v[6:7]
	global_load_dwordx4 v[32:35], v[6:7], off
	v_ashrrev_i32_e32 v4, 5, v167
	v_ashrrev_i32_e32 v5, 31, v4
	v_lshlrev_b64 v[6:7], 9, v[4:5]
	v_lshl_add_u64 v[6:7], v[8:9], 0, v[6:7]
	global_load_dwordx4 v[36:39], v[6:7], off
	v_ashrrev_i32_e32 v4, 5, v168
	v_ashrrev_i32_e32 v5, 31, v4
	v_lshlrev_b64 v[6:7], 9, v[4:5]
	v_lshl_add_u64 v[6:7], v[8:9], 0, v[6:7]
	global_load_dwordx4 v[40:43], v[6:7], off
	v_ashrrev_i32_e32 v4, 5, v169
	v_ashrrev_i32_e32 v5, 31, v4
	v_lshlrev_b64 v[6:7], 9, v[4:5]
	v_lshl_add_u64 v[6:7], v[8:9], 0, v[6:7]
	global_load_dwordx4 v[44:47], v[6:7], off
	v_ashrrev_i32_e32 v4, 5, v1
	v_ashrrev_i32_e32 v5, 31, v4
	v_lshlrev_b64 v[6:7], 9, v[4:5]
	v_lshl_add_u64 v[6:7], v[8:9], 0, v[6:7]
	global_load_dwordx4 v[48:51], v[6:7], off
	v_add_u32_e32 v1, 0x900, v159
	v_ashrrev_i32_e32 v4, 5, v1
	v_ashrrev_i32_e32 v5, 31, v4
	v_lshlrev_b64 v[6:7], 9, v[4:5]
	v_lshl_add_u64 v[6:7], v[8:9], 0, v[6:7]
	global_load_dwordx4 v[52:55], v[6:7], off
	v_add_u32_e32 v1, 0xa00, v159
	v_ashrrev_i32_e32 v4, 5, v1
	v_ashrrev_i32_e32 v5, 31, v4
	v_lshlrev_b64 v[6:7], 9, v[4:5]
	v_lshl_add_u64 v[6:7], v[8:9], 0, v[6:7]
	global_load_dwordx4 v[56:59], v[6:7], off
	v_add_u32_e32 v1, 0xb00, v159
	v_ashrrev_i32_e32 v4, 5, v1
	v_ashrrev_i32_e32 v5, 31, v4
	v_lshlrev_b64 v[6:7], 9, v[4:5]
	v_lshl_add_u64 v[6:7], v[8:9], 0, v[6:7]
	global_load_dwordx4 v[60:63], v[6:7], off
	v_ashrrev_i32_e32 v1, 31, v0
	v_lshl_add_u64 v[112:113], v[0:1], 2, s[62:63]
	s_mov_b32 s12, 0x6dc9c883
	s_mov_b32 s13, 0x3fc45f30
	s_waitcnt vmcnt(11)
	ds_write_b128 v10, v[16:19]
	s_waitcnt vmcnt(10)
	ds_write_b128 v10, v[20:23] offset:4224
	s_waitcnt vmcnt(9)
	ds_write_b128 v10, v[24:27] offset:8448
	s_waitcnt vmcnt(8)
	ds_write_b128 v10, v[28:31] offset:12672
	s_waitcnt vmcnt(7)
	ds_write_b128 v10, v[32:35] offset:16896
	s_waitcnt vmcnt(6)
	ds_write_b128 v10, v[36:39] offset:21120
	s_waitcnt vmcnt(5)
	ds_write_b128 v10, v[40:43] offset:25344
	s_waitcnt vmcnt(4)
	ds_write_b128 v10, v[44:47] offset:29568
	s_waitcnt vmcnt(3)
	ds_write_b128 v10, v[48:51] offset:33792
	s_waitcnt vmcnt(2)
	ds_write_b128 v10, v[52:55] offset:38016
	s_waitcnt vmcnt(1)
	ds_write_b128 v10, v[56:59] offset:42240
	s_waitcnt vmcnt(0)
	ds_write_b128 v10, v[60:63] offset:46464
	s_waitcnt lgkmcnt(0)
	s_barrier
; DI float bflo(uint32_t u) { return __uint_as_float(u << 16); }
; DI float bfhi(uint32_t u) { return __uint_as_float(u & 0xffff0000u); }
; DI void prep_item(const Params& p, int layer, int item, char* smem) {
;     ...
;   u16* prow = PROJ + (size_t)token * LDP;
;   const float posf = (float)p.pos[token];
;   float cs[8], sn[8];
;   {
;     const float IF0[8] = {1.0f, 0.5623413251903491f, 0.31622776601683794f, 0.1778279410038923f, 0.01f, 0.005623413251903491f, 0.0031622776601683794f, 0.0017782794100389228f};
;     const float IF1[8] = {0.1f, 0.05623413251903491f, 0.03162277660168379f, 0.01778279410038923f, 0.001f, 0.0005623413251903491f, 0.00031622776601683794f, 0.00017782794100389227f};
; #pragma unroll
;     for (int reg = 0; reg < 8; ++reg) {
;       const float inv = h ? IF1[reg] : IF0[reg];
;       const float ang = posf * inv;
;       double rv = (double)ang * 0.15915494309189535;
;       rv -= rint(rv);
;       const float fr = (float)rv;
;       sn[reg] = __builtin_amdgcn_sinf(fr);
;       cs[reg] = __builtin_amdgcn_cosf(fr);
;     }
;   }
;   {
;     bf16x8 bq[16];
;     float ss = 0.f;
; #pragma unroll
;     for (int ks = 0; ks < 16; ++ks) {
;       uint4 u = *(const uint4*)(prow + O_CQ + ks * 16 + 8 * h);
;       bq[ks] = __builtin_bit_cast(bf16x8, u);
;       float f;
;       f = bflo(u.x); ss += f * f; f = bfhi(u.x); ss += f * f; f = bflo(u.y); ss += f * f; f = bfhi(u.y); ss += f * f;
;       f = bflo(u.z); ss += f * f; f = bfhi(u.z); ss += f * f; f = bflo(u.w); ss += f * f; f = bfhi(u.w); ss += f * f;
;     }
	global_load_dword v2, v[112:113], off
	v_mov_b32_e32 v4, 0x3dcccccd
	v_cndmask_b32_e64 v4, v4, 1.0, vcc
	s_waitcnt vmcnt(0)
	v_cvt_f32_i32_e32 v2, v2
	v_mul_f32_e32 v4, v4, v2
	v_cvt_f64_f32_e32 v[4:5], v4
	v_mul_f64 v[6:7], v[4:5], s[12:13]
	v_rndne_f64_e32 v[6:7], v[6:7]
	v_fma_f64 v[4:5], v[4:5], s[12:13], -v[6:7]
	v_cvt_f32_f64_e32 v4, v[4:5]
	v_sin_f32_e32 v116, v4
	v_cos_f32_e32 v118, v4
	v_mov_b32_e32 v4, 0x3d6655c3
	v_mov_b32_e32 v5, 0x3f0ff59a
	v_cndmask_b32_e32 v4, v4, v5, vcc
	v_mul_f32_e32 v4, v4, v2
	v_cvt_f64_f32_e32 v[4:5], v4
	v_mul_f64 v[6:7], v[4:5], s[12:13]
	v_rndne_f64_e32 v[6:7], v[6:7]
	v_fma_f64 v[4:5], v[4:5], s[12:13], -v[6:7]
	v_cvt_f32_f64_e32 v4, v[4:5]
	v_sin_f32_e32 v117, v4
	v_cos_f32_e32 v119, v4
	v_mov_b32_e32 v4, 0x3d0186e2
	v_mov_b32_e32 v5, 0x3ea1e89b
	v_cndmask_b32_e32 v4, v4, v5, vcc
	v_mul_f32_e32 v4, v4, v2
	v_cvt_f64_f32_e32 v[4:5], v4
	v_mul_f64 v[6:7], v[4:5], s[12:13]
	v_rndne_f64_e32 v[6:7], v[6:7]
	v_fma_f64 v[4:5], v[4:5], s[12:13], -v[6:7]
	v_cvt_f32_f64_e32 v4, v[4:5]
	v_sin_f32_e32 v120, v4
	v_cos_f32_e32 v122, v4
	v_mov_b32_e32 v4, 0x3c91ad39
	v_mov_b32_e32 v5, 0x3e361887
	v_cndmask_b32_e32 v4, v4, v5, vcc
	v_mul_f32_e32 v4, v4, v2
	v_cvt_f64_f32_e32 v[4:5], v4
	v_mul_f64 v[6:7], v[4:5], s[12:13]
	v_rndne_f64_e32 v[6:7], v[6:7]
	v_fma_f64 v[4:5], v[4:5], s[12:13], -v[6:7]
	v_cvt_f32_f64_e32 v4, v[4:5]
	v_sin_f32_e32 v121, v4
	v_cos_f32_e32 v123, v4
	v_mov_b32_e32 v4, 0x3a83126f
	v_cndmask_b32_e32 v4, v4, v219, vcc
	v_mul_f32_e32 v4, v4, v2
	v_cvt_f64_f32_e32 v[4:5], v4
	v_mul_f64 v[6:7], v[4:5], s[12:13]
	v_rndne_f64_e32 v[6:7], v[6:7]
	v_fma_f64 v[4:5], v[4:5], s[12:13], -v[6:7]
	v_cvt_f32_f64_e32 v4, v[4:5]
	v_sin_f32_e32 v124, v4
	v_cos_f32_e32 v126, v4
	v_cndmask_b32_e32 v4, v220, v221, vcc
	v_mul_f32_e32 v4, v4, v2
	v_cvt_f64_f32_e32 v[4:5], v4
	v_mul_f64 v[6:7], v[4:5], s[12:13]
	v_rndne_f64_e32 v[6:7], v[6:7]
	v_fma_f64 v[4:5], v[4:5], s[12:13], -v[6:7]
	v_cvt_f32_f64_e32 v4, v[4:5]
	v_sin_f32_e32 v125, v4
	v_cos_f32_e32 v127, v4
	v_cndmask_b32_e32 v4, v222, v223, vcc
	v_mul_f32_e32 v4, v4, v2
	v_cvt_f64_f32_e32 v[4:5], v4
	v_mul_f64 v[6:7], v[4:5], s[12:13]
	v_rndne_f64_e32 v[6:7], v[6:7]
	v_fma_f64 v[4:5], v[4:5], s[12:13], -v[6:7]
	v_cvt_f32_f64_e32 v4, v[4:5]
	v_sin_f32_e32 v150, v4
	v_cos_f32_e32 v152, v4
	v_cndmask_b32_e32 v4, v224, v135, vcc
	v_mul_f32_e32 v2, v4, v2
	v_cvt_f64_f32_e32 v[4:5], v2
	v_mul_f64 v[6:7], v[4:5], s[12:13]
	v_rndne_f64_e32 v[6:7], v[6:7]
	v_fma_f64 v[4:5], v[4:5], s[12:13], -v[6:7]
	v_readlane_b32 s12, v252, 32
	v_readlane_b32 s13, v252, 33
	v_cvt_f32_f64_e32 v2, v[4:5]
	v_sin_f32_e32 v151, v2
	v_mov_b64_e32 v[4:5], s[12:13]
	v_mad_i64_i32 v[114:115], s[12:13], v0, s54, v[4:5]
	v_lshl_add_u64 v[156:157], v[114:115], 0, v[154:155]
	global_load_dwordx4 v[4:7], v[156:157], off
	global_load_dwordx4 v[96:99], v[156:157], off offset:32
	global_load_dwordx4 v[100:103], v[156:157], off offset:64
	global_load_dwordx4 v[108:111], v[156:157], off offset:96
	global_load_dwordx4 v[104:107], v[156:157], off offset:128
	global_load_dwordx4 v[92:95], v[156:157], off offset:160
	global_load_dwordx4 v[88:91], v[156:157], off offset:192
	global_load_dwordx4 v[84:87], v[156:157], off offset:224
	global_load_dwordx4 v[80:83], v[156:157], off offset:256
	global_load_dwordx4 v[76:79], v[156:157], off offset:288
	global_load_dwordx4 v[72:75], v[156:157], off offset:320
	global_load_dwordx4 v[68:71], v[156:157], off offset:352
	global_load_dwordx4 v[64:67], v[156:157], off offset:384
	global_load_dwordx4 v[60:63], v[156:157], off offset:416
	global_load_dwordx4 v[56:59], v[156:157], off offset:448
	global_load_dwordx4 v[52:55], v[156:157], off offset:480
	v_cos_f32_e32 v153, v2
	v_lshlrev_b32_e32 v2, 3, v170
	s_waitcnt vmcnt(15)
	v_lshlrev_b32_e32 v8, 16, v4
	v_mul_f32_e32 v8, v8, v8
	v_and_b32_e32 v9, 0xffff0000, v4
	v_fmac_f32_e32 v8, v9, v9
	v_lshlrev_b32_e32 v9, 16, v5
	v_fmac_f32_e32 v8, v9, v9
	v_and_b32_e32 v9, 0xffff0000, v5
	v_fmac_f32_e32 v8, v9, v9
	v_lshlrev_b32_e32 v9, 16, v6
	v_fmac_f32_e32 v8, v9, v9
	v_and_b32_e32 v9, 0xffff0000, v6
	v_fmac_f32_e32 v8, v9, v9
	v_lshlrev_b32_e32 v9, 16, v7
	v_fmac_f32_e32 v8, v9, v9
	v_and_b32_e32 v9, 0xffff0000, v7
	v_fmac_f32_e32 v8, v9, v9
	s_waitcnt vmcnt(14)
	v_lshlrev_b32_e32 v9, 16, v96
	v_fmac_f32_e32 v8, v9, v9
	v_and_b32_e32 v9, 0xffff0000, v96
	v_fmac_f32_e32 v8, v9, v9
	v_lshlrev_b32_e32 v9, 16, v97
	v_fmac_f32_e32 v8, v9, v9
	v_and_b32_e32 v9, 0xffff0000, v97
	v_fmac_f32_e32 v8, v9, v9
	v_lshlrev_b32_e32 v9, 16, v98
	v_fmac_f32_e32 v8, v9, v9
	v_and_b32_e32 v9, 0xffff0000, v98
	v_fmac_f32_e32 v8, v9, v9
	v_lshlrev_b32_e32 v9, 16, v99
	v_fmac_f32_e32 v8, v9, v9
	v_and_b32_e32 v9, 0xffff0000, v99
	v_fmac_f32_e32 v8, v9, v9
	s_waitcnt vmcnt(13)
	v_lshlrev_b32_e32 v9, 16, v100
	v_fmac_f32_e32 v8, v9, v9
	v_and_b32_e32 v9, 0xffff0000, v100
	v_fmac_f32_e32 v8, v9, v9
	v_lshlrev_b32_e32 v9, 16, v101
	v_fmac_f32_e32 v8, v9, v9
	v_and_b32_e32 v9, 0xffff0000, v101
	v_fmac_f32_e32 v8, v9, v9
	v_lshlrev_b32_e32 v9, 16, v102
	v_fmac_f32_e32 v8, v9, v9
	v_and_b32_e32 v9, 0xffff0000, v102
	v_fmac_f32_e32 v8, v9, v9
	v_lshlrev_b32_e32 v9, 16, v103
	v_fmac_f32_e32 v8, v9, v9
	v_and_b32_e32 v9, 0xffff0000, v103
	v_fmac_f32_e32 v8, v9, v9
	s_waitcnt vmcnt(12)
	v_lshlrev_b32_e32 v9, 16, v108
	v_fmac_f32_e32 v8, v9, v9
	v_and_b32_e32 v9, 0xffff0000, v108
	v_fmac_f32_e32 v8, v9, v9
	v_lshlrev_b32_e32 v9, 16, v109
	v_fmac_f32_e32 v8, v9, v9
	v_and_b32_e32 v9, 0xffff0000, v109
	v_fmac_f32_e32 v8, v9, v9
	v_lshlrev_b32_e32 v9, 16, v110
	v_fmac_f32_e32 v8, v9, v9
	v_and_b32_e32 v9, 0xffff0000, v110
	v_fmac_f32_e32 v8, v9, v9
	v_lshlrev_b32_e32 v9, 16, v111
	v_fmac_f32_e32 v8, v9, v9
	v_and_b32_e32 v9, 0xffff0000, v111
	v_fmac_f32_e32 v8, v9, v9
	s_waitcnt vmcnt(11)
; DI float bflo(uint32_t u) { return __uint_as_float(u << 16); }
; DI float bfhi(uint32_t u) { return __uint_as_float(u & 0xffff0000u); }
; DI void prep_item(const Params& p, int layer, int item, char* smem) {
;     ...
;     for (int ks = 0; ks < 16; ++ks) {
;       uint4 u = *(const uint4*)(prow + O_CQ + ks * 16 + 8 * h);
;       bq[ks] = __builtin_bit_cast(bf16x8, u);
;       float f;
;       f = bflo(u.x); ss += f * f; f = bfhi(u.x); ss += f * f; f = bflo(u.y); ss += f * f; f = bfhi(u.y); ss += f * f;
;       f = bflo(u.z); ss += f * f; f = bfhi(u.z); ss += f * f; f = bflo(u.w); ss += f * f; f = bfhi(u.w); ss += f * f;
;     }
	v_lshlrev_b32_e32 v9, 16, v104
	v_fmac_f32_e32 v8, v9, v9
	v_and_b32_e32 v9, 0xffff0000, v104
	v_fmac_f32_e32 v8, v9, v9
	v_lshlrev_b32_e32 v9, 16, v105
	v_fmac_f32_e32 v8, v9, v9
	v_and_b32_e32 v9, 0xffff0000, v105
	v_fmac_f32_e32 v8, v9, v9
	v_lshlrev_b32_e32 v9, 16, v106
	v_fmac_f32_e32 v8, v9, v9
	v_and_b32_e32 v9, 0xffff0000, v106
	v_fmac_f32_e32 v8, v9, v9
	v_lshlrev_b32_e32 v9, 16, v107
	v_fmac_f32_e32 v8, v9, v9
	v_and_b32_e32 v9, 0xffff0000, v107
	v_fmac_f32_e32 v8, v9, v9
	s_waitcnt vmcnt(10)
	v_lshlrev_b32_e32 v9, 16, v92
	v_fmac_f32_e32 v8, v9, v9
	v_and_b32_e32 v9, 0xffff0000, v92
	v_fmac_f32_e32 v8, v9, v9
	v_lshlrev_b32_e32 v9, 16, v93
	v_fmac_f32_e32 v8, v9, v9
	v_and_b32_e32 v9, 0xffff0000, v93
	v_fmac_f32_e32 v8, v9, v9
	v_lshlrev_b32_e32 v9, 16, v94
	v_fmac_f32_e32 v8, v9, v9
	v_and_b32_e32 v9, 0xffff0000, v94
	v_fmac_f32_e32 v8, v9, v9
	v_lshlrev_b32_e32 v9, 16, v95
	v_fmac_f32_e32 v8, v9, v9
	v_and_b32_e32 v9, 0xffff0000, v95
	v_fmac_f32_e32 v8, v9, v9
	s_waitcnt vmcnt(9)
	v_lshlrev_b32_e32 v9, 16, v88
	v_fmac_f32_e32 v8, v9, v9
	v_and_b32_e32 v9, 0xffff0000, v88
	v_fmac_f32_e32 v8, v9, v9
	v_lshlrev_b32_e32 v9, 16, v89
	v_fmac_f32_e32 v8, v9, v9
	v_and_b32_e32 v9, 0xffff0000, v89
	v_fmac_f32_e32 v8, v9, v9
	v_lshlrev_b32_e32 v9, 16, v90
	v_fmac_f32_e32 v8, v9, v9
	v_and_b32_e32 v9, 0xffff0000, v90
	v_fmac_f32_e32 v8, v9, v9
	v_lshlrev_b32_e32 v9, 16, v91
	v_fmac_f32_e32 v8, v9, v9
	v_and_b32_e32 v9, 0xffff0000, v91
	v_fmac_f32_e32 v8, v9, v9
	s_waitcnt vmcnt(8)
	v_lshlrev_b32_e32 v9, 16, v84
	v_fmac_f32_e32 v8, v9, v9
	v_and_b32_e32 v9, 0xffff0000, v84
	v_fmac_f32_e32 v8, v9, v9
	v_lshlrev_b32_e32 v9, 16, v85
	v_fmac_f32_e32 v8, v9, v9
	v_and_b32_e32 v9, 0xffff0000, v85
	v_fmac_f32_e32 v8, v9, v9
	v_lshlrev_b32_e32 v9, 16, v86
	v_fmac_f32_e32 v8, v9, v9
	v_and_b32_e32 v9, 0xffff0000, v86
	v_fmac_f32_e32 v8, v9, v9
	v_lshlrev_b32_e32 v9, 16, v87
	v_fmac_f32_e32 v8, v9, v9
	v_and_b32_e32 v9, 0xffff0000, v87
	v_fmac_f32_e32 v8, v9, v9
	s_waitcnt vmcnt(7)
	v_lshlrev_b32_e32 v9, 16, v80
	v_fmac_f32_e32 v8, v9, v9
	v_and_b32_e32 v9, 0xffff0000, v80
	v_fmac_f32_e32 v8, v9, v9
	v_lshlrev_b32_e32 v9, 16, v81
	v_fmac_f32_e32 v8, v9, v9
	v_and_b32_e32 v9, 0xffff0000, v81
	v_fmac_f32_e32 v8, v9, v9
	v_lshlrev_b32_e32 v9, 16, v82
	v_fmac_f32_e32 v8, v9, v9
	v_and_b32_e32 v9, 0xffff0000, v82
	v_fmac_f32_e32 v8, v9, v9
	v_lshlrev_b32_e32 v9, 16, v83
	v_fmac_f32_e32 v8, v9, v9
	v_and_b32_e32 v9, 0xffff0000, v83
	v_fmac_f32_e32 v8, v9, v9
	s_waitcnt vmcnt(6)
	v_lshlrev_b32_e32 v9, 16, v76
	v_fmac_f32_e32 v8, v9, v9
	v_and_b32_e32 v9, 0xffff0000, v76
	v_fmac_f32_e32 v8, v9, v9
	v_lshlrev_b32_e32 v9, 16, v77
	v_fmac_f32_e32 v8, v9, v9
	v_and_b32_e32 v9, 0xffff0000, v77
	v_fmac_f32_e32 v8, v9, v9
	v_lshlrev_b32_e32 v9, 16, v78
	v_fmac_f32_e32 v8, v9, v9
	v_and_b32_e32 v9, 0xffff0000, v78
	v_fmac_f32_e32 v8, v9, v9
	v_lshlrev_b32_e32 v9, 16, v79
	v_fmac_f32_e32 v8, v9, v9
	v_and_b32_e32 v9, 0xffff0000, v79
	v_fmac_f32_e32 v8, v9, v9
	s_waitcnt vmcnt(5)
	v_lshlrev_b32_e32 v9, 16, v72
	v_fmac_f32_e32 v8, v9, v9
	v_and_b32_e32 v9, 0xffff0000, v72
	v_fmac_f32_e32 v8, v9, v9
	v_lshlrev_b32_e32 v9, 16, v73
	v_fmac_f32_e32 v8, v9, v9
	v_and_b32_e32 v9, 0xffff0000, v73
	v_fmac_f32_e32 v8, v9, v9
	v_lshlrev_b32_e32 v9, 16, v74
	v_fmac_f32_e32 v8, v9, v9
	v_and_b32_e32 v9, 0xffff0000, v74
	v_fmac_f32_e32 v8, v9, v9
	v_lshlrev_b32_e32 v9, 16, v75
	v_fmac_f32_e32 v8, v9, v9
	v_and_b32_e32 v9, 0xffff0000, v75
	v_fmac_f32_e32 v8, v9, v9
	s_waitcnt vmcnt(4)
	v_lshlrev_b32_e32 v9, 16, v68
	v_fmac_f32_e32 v8, v9, v9
	v_and_b32_e32 v9, 0xffff0000, v68
	v_fmac_f32_e32 v8, v9, v9
	v_lshlrev_b32_e32 v9, 16, v69
	v_fmac_f32_e32 v8, v9, v9
	v_and_b32_e32 v9, 0xffff0000, v69
	v_fmac_f32_e32 v8, v9, v9
	v_lshlrev_b32_e32 v9, 16, v70
	v_fmac_f32_e32 v8, v9, v9
	v_and_b32_e32 v9, 0xffff0000, v70
	v_fmac_f32_e32 v8, v9, v9
	v_lshlrev_b32_e32 v9, 16, v71
	v_fmac_f32_e32 v8, v9, v9
	v_and_b32_e32 v9, 0xffff0000, v71
	v_fmac_f32_e32 v8, v9, v9
	s_waitcnt vmcnt(3)
	v_lshlrev_b32_e32 v9, 16, v64
	v_fmac_f32_e32 v8, v9, v9
	v_and_b32_e32 v9, 0xffff0000, v64
	v_fmac_f32_e32 v8, v9, v9
	v_lshlrev_b32_e32 v9, 16, v65
	v_fmac_f32_e32 v8, v9, v9
	v_and_b32_e32 v9, 0xffff0000, v65
	v_fmac_f32_e32 v8, v9, v9
	v_lshlrev_b32_e32 v9, 16, v66
	v_fmac_f32_e32 v8, v9, v9
	v_and_b32_e32 v9, 0xffff0000, v66
	v_fmac_f32_e32 v8, v9, v9
	v_lshlrev_b32_e32 v9, 16, v67
	v_fmac_f32_e32 v8, v9, v9
	v_and_b32_e32 v9, 0xffff0000, v67
	v_fmac_f32_e32 v8, v9, v9
	s_waitcnt vmcnt(2)
	v_lshlrev_b32_e32 v9, 16, v60
	v_fmac_f32_e32 v8, v9, v9
	v_and_b32_e32 v9, 0xffff0000, v60
	v_fmac_f32_e32 v8, v9, v9
	v_lshlrev_b32_e32 v9, 16, v61
	v_fmac_f32_e32 v8, v9, v9
	v_and_b32_e32 v9, 0xffff0000, v61
	v_fmac_f32_e32 v8, v9, v9
	v_lshlrev_b32_e32 v9, 16, v62
	v_fmac_f32_e32 v8, v9, v9
	v_and_b32_e32 v9, 0xffff0000, v62
	v_fmac_f32_e32 v8, v9, v9
	v_lshlrev_b32_e32 v9, 16, v63
	v_fmac_f32_e32 v8, v9, v9
	v_and_b32_e32 v9, 0xffff0000, v63
	v_fmac_f32_e32 v8, v9, v9
	s_waitcnt vmcnt(1)
	v_lshlrev_b32_e32 v9, 16, v56
	v_fmac_f32_e32 v8, v9, v9
	v_and_b32_e32 v9, 0xffff0000, v56
	v_fmac_f32_e32 v8, v9, v9
	v_lshlrev_b32_e32 v9, 16, v57
	v_fmac_f32_e32 v8, v9, v9
	v_and_b32_e32 v9, 0xffff0000, v57
	v_fmac_f32_e32 v8, v9, v9
	v_lshlrev_b32_e32 v9, 16, v58
	v_fmac_f32_e32 v8, v9, v9
	v_and_b32_e32 v9, 0xffff0000, v58
	v_and_b32_e32 v10, 0xffff0000, v59
	v_lshlrev_b32_e32 v11, 16, v59
	v_fmac_f32_e32 v8, v9, v9
	v_pk_mul_f32 v[10:11], v[10:11], v[10:11]
	s_waitcnt vmcnt(0)
; #define MFMA32(a, b, c) __builtin_amdgcn_mfma_f32_32x32x16_bf16((a), (b), (c), 0, 0, 0)
; DI float bflo(uint32_t u) { return __uint_as_float(u << 16); }
; DI float bfhi(uint32_t u) { return __uint_as_float(u & 0xffff0000u); }
; DI float xor32(float v) { return __shfl_xor(v, 32); }
; DI f32x16 zero16() { f32x16 z; _Pragma("unroll") for (int i = 0; i < 16; ++i) z[i] = 0.f; return z; }
; DI void prep_item(const Params& p, int layer, int item, char* smem) {
;     ...
;     for (int ks = 0; ks < 16; ++ks) {
;       uint4 u = *(const uint4*)(prow + O_CQ + ks * 16 + 8 * h);
;       bq[ks] = __builtin_bit_cast(bf16x8, u);
;       float f;
;       f = bflo(u.x); ss += f * f; f = bfhi(u.x); ss += f * f; f = bflo(u.y); ss += f * f; f = bfhi(u.y); ss += f * f;
;       f = bflo(u.z); ss += f * f; f = bfhi(u.z); ss += f * f; f = bflo(u.w); ss += f * f; f = bfhi(u.w); ss += f * f;
;     }
;     ss += xor32(ss);
;     const float rq = rsqrtf(ss * (1.f / 256.f) + EPS);
;     f32x16 acc[3];
;     acc[0] = zero16(); acc[1] = zero16(); acc[2] = zero16();
; #pragma unroll
;     for (int ks = 0; ks < 16; ++ks) {
; #pragma unroll
;       for (int nt = 0; nt < 3; ++nt) {
;         bf16x8 a = *(const bf16x8*)&sWq[nt * 32 + r][ks * 16 + 8 * h];
;         acc[nt] = MFMA32(a, bq[ks], acc[nt]);
;       }
;     }
	v_lshlrev_b32_e32 v9, 16, v52
	v_add_f32_e32 v8, v11, v8
	v_add_f32_e32 v10, v10, v8
	v_and_b32_e32 v8, 0xffff0000, v52
	v_pk_mul_f32 v[8:9], v[8:9], v[8:9]
	s_nop 0
	v_add_f32_e32 v9, v9, v10
	v_add_f32_e32 v10, v8, v9
	v_and_b32_e32 v8, 0xffff0000, v53
	v_lshlrev_b32_e32 v9, 16, v53
	v_pk_mul_f32 v[8:9], v[8:9], v[8:9]
	s_nop 0
	v_add_f32_e32 v9, v9, v10
	v_add_f32_e32 v10, v8, v9
	v_and_b32_e32 v8, 0xffff0000, v54
	v_lshlrev_b32_e32 v9, 16, v54
	v_pk_mul_f32 v[8:9], v[8:9], v[8:9]
	s_nop 0
	v_add_f32_e32 v9, v9, v10
	v_add_f32_e32 v10, v8, v9
	v_and_b32_e32 v8, 0xffff0000, v55
	v_lshlrev_b32_e32 v9, 16, v55
	v_pk_mul_f32 v[8:9], v[8:9], v[8:9]
	s_nop 0
	v_add_f32_e32 v9, v9, v10
	v_and_b32_e32 v10, 64, v213
	v_add_f32_e32 v8, v8, v9
	v_xor_b32_e32 v9, 32, v213
	v_add_u32_e32 v160, 64, v10
	v_cmp_lt_i32_e32 vcc, v9, v160
	s_nop 1
	v_cndmask_b32_e32 v9, v213, v9, vcc
	v_lshlrev_b32_e32 v155, 2, v9
	ds_bpermute_b32 v9, v155, v8
	s_waitcnt lgkmcnt(0)
	v_add_f32_e32 v8, v8, v9
	v_fmamk_f32 v8, v8, 0x3b800000, v206
	v_cmp_gt_f32_e32 vcc, s30, v8
	v_mul_f32_e32 v9, 0x4b800000, v8
	s_nop 0
	v_cndmask_b32_e32 v8, v8, v9, vcc
	v_rsq_f32_e32 v171, v8
	ds_read_b128 v[8:11], v173
	ds_read_b128 v[174:177], v173 offset:32
	s_waitcnt lgkmcnt(1)
	v_mfma_f32_32x32x16_bf16 v[36:51], v[8:11], v[4:7], 0
	ds_read_b128 v[8:11], v173 offset:16896
	v_mul_f32_e32 v172, 0x45800000, v171
	s_waitcnt lgkmcnt(1)
	v_mfma_f32_32x32x16_bf16 v[36:51], v[174:177], v[96:99], v[36:51]
	ds_read_b128 v[174:177], v173 offset:16928
	s_waitcnt lgkmcnt(1)
	v_mfma_f32_32x32x16_bf16 v[20:35], v[8:11], v[4:7], 0
	ds_read_b128 v[8:11], v173 offset:33792
	s_waitcnt lgkmcnt(1)
	v_mfma_f32_32x32x16_bf16 v[20:35], v[174:177], v[96:99], v[20:35]
	ds_read_b128 v[174:177], v173 offset:33824
	s_waitcnt lgkmcnt(1)
	v_mfma_f32_32x32x16_bf16 v[4:19], v[8:11], v[4:7], 0
	s_waitcnt lgkmcnt(0)
	v_mfma_f32_32x32x16_bf16 v[4:19], v[174:177], v[96:99], v[4:19]
	ds_read_b128 v[96:99], v173 offset:64
	s_waitcnt lgkmcnt(0)
	v_mfma_f32_32x32x16_bf16 v[36:51], v[96:99], v[100:103], v[36:51]
	ds_read_b128 v[96:99], v173 offset:16960
	s_waitcnt lgkmcnt(0)
	v_mfma_f32_32x32x16_bf16 v[20:35], v[96:99], v[100:103], v[20:35]
	ds_read_b128 v[96:99], v173 offset:33856
	s_waitcnt lgkmcnt(0)
	v_mfma_f32_32x32x16_bf16 v[4:19], v[96:99], v[100:103], v[4:19]
	ds_read_b128 v[96:99], v173 offset:96
	s_waitcnt lgkmcnt(0)
	v_mfma_f32_32x32x16_bf16 v[36:51], v[96:99], v[108:111], v[36:51]
	ds_read_b128 v[96:99], v173 offset:16992
	s_waitcnt lgkmcnt(0)
	v_mfma_f32_32x32x16_bf16 v[20:35], v[96:99], v[108:111], v[20:35]
	ds_read_b128 v[96:99], v173 offset:33888
	s_waitcnt lgkmcnt(0)
	v_mfma_f32_32x32x16_bf16 v[4:19], v[96:99], v[108:111], v[4:19]
	ds_read_b128 v[96:99], v173 offset:128
	s_waitcnt lgkmcnt(0)
	v_mfma_f32_32x32x16_bf16 v[36:51], v[96:99], v[104:107], v[36:51]
	ds_read_b128 v[96:99], v173 offset:17024
	s_waitcnt lgkmcnt(0)
	v_mfma_f32_32x32x16_bf16 v[20:35], v[96:99], v[104:107], v[20:35]
	ds_read_b128 v[96:99], v173 offset:33920
	s_waitcnt lgkmcnt(0)
	v_mfma_f32_32x32x16_bf16 v[4:19], v[96:99], v[104:107], v[4:19]
	ds_read_b128 v[96:99], v173 offset:160
	s_waitcnt lgkmcnt(0)
	v_mfma_f32_32x32x16_bf16 v[36:51], v[96:99], v[92:95], v[36:51]
	ds_read_b128 v[96:99], v173 offset:17056
	s_waitcnt lgkmcnt(0)
	v_mfma_f32_32x32x16_bf16 v[20:35], v[96:99], v[92:95], v[20:35]
	ds_read_b128 v[96:99], v173 offset:33952
	s_waitcnt lgkmcnt(0)
	v_mfma_f32_32x32x16_bf16 v[4:19], v[96:99], v[92:95], v[4:19]
	ds_read_b128 v[92:95], v173 offset:192
	v_bitop3_b32 v97, s5, v225, v161 bitop3:0xc8
	s_ashr_i32 s5, s0, 4
	s_and_b32 s5, s5, -8
	s_or_b32 s12, s5, s1
	s_ashr_i32 s13, s12, 31
	s_lshl_b64 s[14:15], s[12:13], 12
	s_waitcnt lgkmcnt(0)
	v_mfma_f32_32x32x16_bf16 v[36:51], v[92:95], v[88:91], v[36:51]
	ds_read_b128 v[92:95], v173 offset:17088
	v_or_b32_e32 v98, s14, v97
	s_movk_i32 s13, 0xc0
	v_lshlrev_b32_e32 v96, 2, v170
	s_mov_b32 s14, 0x3e16c740
	s_lshl_b32 s5, s1, 15
	s_waitcnt lgkmcnt(0)
	v_mfma_f32_32x32x16_bf16 v[20:35], v[92:95], v[88:91], v[20:35]
	ds_read_b128 v[92:95], v173 offset:33984
	s_waitcnt lgkmcnt(0)
	v_mfma_f32_32x32x16_bf16 v[4:19], v[92:95], v[88:91], v[4:19]
	ds_read_b128 v[88:91], v173 offset:224
	s_waitcnt lgkmcnt(0)
	v_mfma_f32_32x32x16_bf16 v[36:51], v[88:91], v[84:87], v[36:51]
	ds_read_b128 v[88:91], v173 offset:17120
	s_waitcnt lgkmcnt(0)
	v_mfma_f32_32x32x16_bf16 v[20:35], v[88:91], v[84:87], v[20:35]
	ds_read_b128 v[88:91], v173 offset:34016
	s_waitcnt lgkmcnt(0)
	v_mfma_f32_32x32x16_bf16 v[4:19], v[88:91], v[84:87], v[4:19]
	ds_read_b128 v[84:87], v173 offset:256
	s_waitcnt lgkmcnt(0)
	v_mfma_f32_32x32x16_bf16 v[36:51], v[84:87], v[80:83], v[36:51]
	ds_read_b128 v[84:87], v173 offset:17152
	s_waitcnt lgkmcnt(0)
	v_mfma_f32_32x32x16_bf16 v[20:35], v[84:87], v[80:83], v[20:35]
	ds_read_b128 v[84:87], v173 offset:34048
	s_waitcnt lgkmcnt(0)
	v_mfma_f32_32x32x16_bf16 v[4:19], v[84:87], v[80:83], v[4:19]
	ds_read_b128 v[80:83], v173 offset:288
	s_waitcnt lgkmcnt(0)
	v_mfma_f32_32x32x16_bf16 v[36:51], v[80:83], v[76:79], v[36:51]
	ds_read_b128 v[80:83], v173 offset:17184
	s_waitcnt lgkmcnt(0)
	v_mfma_f32_32x32x16_bf16 v[20:35], v[80:83], v[76:79], v[20:35]
	ds_read_b128 v[80:83], v173 offset:34080
	s_waitcnt lgkmcnt(0)
	v_mfma_f32_32x32x16_bf16 v[4:19], v[80:83], v[76:79], v[4:19]
	ds_read_b128 v[76:79], v173 offset:320
	s_waitcnt lgkmcnt(0)
	v_mfma_f32_32x32x16_bf16 v[36:51], v[76:79], v[72:75], v[36:51]
	ds_read_b128 v[76:79], v173 offset:17216
	s_waitcnt lgkmcnt(0)
	v_mfma_f32_32x32x16_bf16 v[20:35], v[76:79], v[72:75], v[20:35]
	ds_read_b128 v[76:79], v173 offset:34112
	s_waitcnt lgkmcnt(0)
; #define MFMA32(a, b, c) __builtin_amdgcn_mfma_f32_32x32x16_bf16((a), (b), (c), 0, 0, 0)
; DI float xor32(float v) { return __shfl_xor(v, 32); }
; DI void prep_item(const Params& p, int layer, int item, char* smem) {
;     ...
;     for (int ks = 0; ks < 16; ++ks) {
; #pragma unroll
;       for (int nt = 0; nt < 3; ++nt) {
;         bf16x8 a = *(const bf16x8*)&sWq[nt * 32 + r][ks * 16 + 8 * h];
;         acc[nt] = MFMA32(a, bq[ks], acc[nt]);
;       }
;     }
;     float ss2 = 0.f;
; #pragma unroll
;     for (int nt = 0; nt < 3; ++nt)
; #pragma unroll
;       for (int i = 0; i < 16; ++i) { acc[nt][i] *= rq; ss2 += acc[nt][i] * acc[nt][i]; }
;     ss2 += xor32(ss2);
;     const float r2 = rsqrtf(ss2 * (1.f / 96.f) + EPS);
;     const float* gq = p.mla_q_g + layer * 96;
; #pragma unroll
;     for (int nt = 0; nt < 3; ++nt)
; #pragma unroll
;       for (int g = 0; g < 4; ++g) {
;         float4 gg = *(const float4*)(gq + nt * 32 + 8 * g + 4 * h);
;         acc[nt][4 * g] *= r2 * gg.x; acc[nt][4 * g + 1] *= r2 * gg.y; acc[nt][4 * g + 2] *= r2 * gg.z; acc[nt][4 * g + 3] *= r2 * gg.w;
;       }
	v_mfma_f32_32x32x16_bf16 v[4:19], v[76:79], v[72:75], v[4:19]
	ds_read_b128 v[72:75], v173 offset:352
	s_waitcnt lgkmcnt(0)
	v_mfma_f32_32x32x16_bf16 v[36:51], v[72:75], v[68:71], v[36:51]
	ds_read_b128 v[72:75], v173 offset:17248
	s_waitcnt lgkmcnt(0)
	v_mfma_f32_32x32x16_bf16 v[20:35], v[72:75], v[68:71], v[20:35]
	ds_read_b128 v[72:75], v173 offset:34144
	s_waitcnt lgkmcnt(0)
	v_mfma_f32_32x32x16_bf16 v[4:19], v[72:75], v[68:71], v[4:19]
	ds_read_b128 v[68:71], v173 offset:384
	v_cndmask_b32_e32 v72, v171, v172, vcc
	s_waitcnt lgkmcnt(0)
	v_mfma_f32_32x32x16_bf16 v[36:51], v[68:71], v[64:67], v[36:51]
	ds_read_b128 v[68:71], v173 offset:17280
	s_waitcnt lgkmcnt(0)
	v_mfma_f32_32x32x16_bf16 v[20:35], v[68:71], v[64:67], v[20:35]
	ds_read_b128 v[68:71], v173 offset:34176
	s_waitcnt lgkmcnt(0)
	v_mfma_f32_32x32x16_bf16 v[4:19], v[68:71], v[64:67], v[4:19]
	ds_read_b128 v[64:67], v173 offset:416
	s_waitcnt lgkmcnt(0)
	v_mfma_f32_32x32x16_bf16 v[36:51], v[64:67], v[60:63], v[36:51]
	ds_read_b128 v[64:67], v173 offset:17312
	s_waitcnt lgkmcnt(0)
	v_mfma_f32_32x32x16_bf16 v[20:35], v[64:67], v[60:63], v[20:35]
	ds_read_b128 v[64:67], v173 offset:34208
	s_waitcnt lgkmcnt(0)
	v_mfma_f32_32x32x16_bf16 v[4:19], v[64:67], v[60:63], v[4:19]
	ds_read_b128 v[60:63], v173 offset:448
	global_load_dwordx4 v[64:67], v154, s[36:37] offset:32
	s_waitcnt lgkmcnt(0)
	v_mfma_f32_32x32x16_bf16 v[36:51], v[60:63], v[56:59], v[36:51]
	ds_read_b128 v[60:63], v173 offset:17344
	s_waitcnt lgkmcnt(0)
	v_mfma_f32_32x32x16_bf16 v[20:35], v[60:63], v[56:59], v[20:35]
	ds_read_b128 v[60:63], v173 offset:34240
	s_waitcnt lgkmcnt(0)
	v_mfma_f32_32x32x16_bf16 v[4:19], v[60:63], v[56:59], v[4:19]
	ds_read_b128 v[56:59], v173 offset:480
	s_waitcnt lgkmcnt(0)
	v_mfma_f32_32x32x16_bf16 v[36:51], v[56:59], v[52:55], v[36:51]
	ds_read_b128 v[56:59], v173 offset:17376
	s_waitcnt lgkmcnt(0)
	v_mfma_f32_32x32x16_bf16 v[20:35], v[56:59], v[52:55], v[20:35]
	ds_read_b128 v[56:59], v173 offset:34272
	s_nop 7
	v_mul_f32_e64 v78, v42, v72
	v_mul_f32_e64 v79, v43, v72
	v_mul_f32_e64 v82, v40, v72
	v_mul_f32_e64 v83, v41, v72
	global_load_dwordx4 v[40:43], v154, s[36:37] offset:64
	v_pk_mul_f32 v[86:87], v[46:47], v[72:73] op_sel_hi:[1,0]
	v_pk_mul_f32 v[90:91], v[44:45], v[72:73] op_sel_hi:[1,0]
	global_load_dwordx4 v[44:47], v154, s[36:37] offset:96
	s_waitcnt lgkmcnt(0)
	v_mfma_f32_32x32x16_bf16 v[4:19], v[56:59], v[52:55], v[4:19]
	v_mul_f32_e64 v94, v50, v72
	v_mul_f32_e64 v95, v51, v72
	v_mul_f32_e64 v102, v48, v72
	v_mul_f32_e64 v103, v49, v72
	global_load_dwordx4 v[48:51], v154, s[36:37] offset:128
	v_pk_mul_f32 v[106:107], v[22:23], v[72:73] op_sel_hi:[1,0]
	v_pk_mul_f32 v[110:111], v[20:21], v[72:73] op_sel_hi:[1,0]
	global_load_dwordx4 v[20:23], v154, s[36:37] offset:160
	v_pk_mul_f32 v[132:133], v[26:27], v[72:73] op_sel_hi:[1,0]
	s_nop 2
	v_pk_mul_f32 v[52:53], v[14:15], v[72:73] op_sel_hi:[1,0]
	v_mov_b64_e32 v[14:15], s[20:21]
	v_mad_u64_u32 v[14:15], s[18:19], v98, s13, v[14:15]
	v_mad_i32_i24 v15, s15, v212, v15
	v_pk_mul_f32 v[54:55], v[16:17], v[72:73] op_sel_hi:[1,0]
	v_pk_mul_f32 v[56:57], v[18:19], v[72:73] op_sel_hi:[1,0]
	v_lshl_add_u64 v[18:19], v[14:15], 0, v[2:3]
	global_load_dwordx4 v[14:17], v154, s[36:37]
	v_pk_mul_f32 v[172:173], v[24:25], v[72:73] op_sel_hi:[1,0]
	global_load_dwordx4 v[24:27], v154, s[36:37] offset:192
	v_pk_mul_f32 v[176:177], v[30:31], v[72:73] op_sel_hi:[1,0]
	v_pk_mul_f32 v[180:181], v[28:29], v[72:73] op_sel_hi:[1,0]
	v_pk_mul_f32 v[184:185], v[34:35], v[72:73] op_sel_hi:[1,0]
	global_load_dwordx4 v[28:31], v154, s[36:37] offset:224
	v_pk_mul_f32 v[188:189], v[32:33], v[72:73] op_sel_hi:[1,0]
	v_pk_mul_f32 v[192:193], v[6:7], v[72:73] op_sel_hi:[1,0]
	global_load_dwordx4 v[32:35], v154, s[36:37] offset:256
	global_load_dwordx4 v[68:71], v154, s[36:37] offset:320
	v_pk_mul_f32 v[196:197], v[4:5], v[72:73] op_sel_hi:[1,0]
	v_pk_mul_f32 v[200:201], v[12:13], v[72:73] op_sel_hi:[1,0]
	v_pk_mul_f32 v[232:233], v[10:11], v[72:73] op_sel_hi:[1,0]
	global_load_dwordx4 v[4:7], v154, s[36:37] offset:288
	global_load_dwordx4 v[10:13], v154, s[36:37] offset:352
	v_pk_mul_f32 v[36:37], v[36:37], v[72:73] op_sel_hi:[1,0]
	v_pk_mul_f32 v[38:39], v[38:39], v[72:73] op_sel_hi:[1,0]
	v_pk_mul_f32 v[76:77], v[36:37], v[36:37]
	v_pk_mul_f32 v[74:75], v[38:39], v[38:39]
	v_add_f32_e32 v76, v76, v77
	v_add_f32_e32 v74, v74, v76
	v_pk_mul_f32 v[84:85], v[82:83], v[82:83]
	v_add_f32_e32 v74, v75, v74
	v_add_f32_e32 v74, v84, v74
	v_pk_mul_f32 v[80:81], v[78:79], v[78:79]
	v_add_f32_e32 v74, v85, v74
	v_add_f32_e32 v74, v80, v74
	v_pk_mul_f32 v[92:93], v[90:91], v[90:91]
	v_add_f32_e32 v74, v81, v74
	v_add_f32_e32 v74, v92, v74
	v_pk_mul_f32 v[88:89], v[86:87], v[86:87]
	v_add_f32_e32 v74, v93, v74
	v_add_f32_e32 v74, v88, v74
	v_pk_mul_f32 v[104:105], v[102:103], v[102:103]
	v_add_f32_e32 v74, v89, v74
	v_add_f32_e32 v74, v104, v74
	v_pk_mul_f32 v[100:101], v[94:95], v[94:95]
	v_add_f32_e32 v74, v105, v74
	v_add_f32_e32 v74, v100, v74
	v_pk_mul_f32 v[130:131], v[110:111], v[110:111]
	v_add_f32_e32 v74, v101, v74
	v_add_f32_e32 v74, v130, v74
	v_pk_mul_f32 v[108:109], v[106:107], v[106:107]
	v_add_f32_e32 v74, v131, v74
	v_add_f32_e32 v74, v108, v74
	v_pk_mul_f32 v[174:175], v[172:173], v[172:173]
	v_add_f32_e32 v74, v109, v74
	v_add_f32_e32 v74, v174, v74
	v_pk_mul_f32 v[170:171], v[132:133], v[132:133]
	v_add_f32_e32 v74, v175, v74
	v_add_f32_e32 v74, v170, v74
	v_pk_mul_f32 v[182:183], v[180:181], v[180:181]
	v_add_f32_e32 v74, v171, v74
	v_add_f32_e32 v74, v182, v74
	v_pk_mul_f32 v[178:179], v[176:177], v[176:177]
	v_add_f32_e32 v74, v183, v74
	v_add_f32_e32 v74, v178, v74
	v_pk_mul_f32 v[190:191], v[188:189], v[188:189]
	v_add_f32_e32 v74, v179, v74
	v_add_f32_e32 v74, v190, v74
	v_pk_mul_f32 v[186:187], v[184:185], v[184:185]
	v_add_f32_e32 v74, v191, v74
	v_add_f32_e32 v74, v186, v74
	v_pk_mul_f32 v[198:199], v[196:197], v[196:197]
	v_add_f32_e32 v74, v187, v74
	v_add_f32_e32 v74, v198, v74
	v_pk_mul_f32 v[194:195], v[192:193], v[192:193]
	v_add_f32_e32 v74, v199, v74
	v_pk_mul_f32 v[8:9], v[8:9], v[72:73] op_sel_hi:[1,0]
	v_add_f32_e32 v74, v194, v74
	v_pk_mul_f32 v[72:73], v[8:9], v[8:9]
	v_add_f32_e32 v74, v195, v74
	v_add_f32_e32 v72, v72, v74
	v_pk_mul_f32 v[234:235], v[232:233], v[232:233]
	v_add_f32_e32 v72, v73, v72
	v_add_f32_e32 v72, v234, v72
	v_pk_mul_f32 v[230:231], v[200:201], v[200:201]
	v_add_f32_e32 v72, v235, v72
	v_add_f32_e32 v72, v230, v72
	v_pk_mul_f32 v[58:59], v[52:53], v[52:53]
	v_add_f32_e32 v72, v231, v72
	v_add_f32_e32 v58, v58, v72
	v_pk_mul_f32 v[60:61], v[54:55], v[54:55]
	v_add_f32_e32 v58, v59, v58
	v_add_f32_e32 v58, v60, v58
	v_pk_mul_f32 v[62:63], v[56:57], v[56:57]
	v_add_f32_e32 v58, v61, v58
	v_add_f32_e32 v58, v62, v58
	v_add_f32_e32 v58, v63, v58
	ds_bpermute_b32 v59, v155, v58
	s_waitcnt lgkmcnt(0)
; DI uint32_t pack2(float a, float b) { f2_t v = {a, b}; bf2_t r = __builtin_convertvector(v, bf2_t); return __builtin_bit_cast(uint32_t, r); }
; DI float xor32(float v) { return __shfl_xor(v, 32); }
; DI void prep_item(const Params& p, int layer, int item, char* smem) {
;     ...
;     ss2 += xor32(ss2);
;     const float r2 = rsqrtf(ss2 * (1.f / 96.f) + EPS);
;     const float* gq = p.mla_q_g + layer * 96;
; #pragma unroll
;     for (int nt = 0; nt < 3; ++nt)
; #pragma unroll
;       for (int g = 0; g < 4; ++g) {
;         float4 gg = *(const float4*)(gq + nt * 32 + 8 * g + 4 * h);
;         acc[nt][4 * g] *= r2 * gg.x; acc[nt][4 * g + 1] *= r2 * gg.y; acc[nt][4 * g + 2] *= r2 * gg.z; acc[nt][4 * g + 3] *= r2 * gg.w;
;       }
; #pragma unroll
;     for (int reg = 0; reg < 8; ++reg) {
;       float x1 = acc[2][reg], x2 = acc[2][reg + 8];
;       acc[2][reg] = x1 * cs[reg] - x2 * sn[reg];
;       acc[2][reg + 8] = x2 * cs[reg] + x1 * sn[reg];
;     }
;     u16* qo = QB + ((size_t)(b * 8 + hd) * 4096 + s) * 96;
; #pragma unroll
;     for (int nt = 0; nt < 3; ++nt)
; #pragma unroll
;       for (int g = 0; g < 4; ++g)
;         *(uint2*)(qo + nt * 32 + 8 * g + 4 * h) = make_uint2(pack2(acc[nt][4 * g] * C_MLA, acc[nt][4 * g + 1] * C_MLA), pack2(acc[nt][4 * g + 2] * C_MLA, acc[nt][4 * g + 3] * C_MLA));
;   }
;   __syncthreads();
;   {
;     const u16* src = WUKV + (size_t)(hd * 128) * 128;
	v_add_f32_e32 v58, v58, v59
	v_fmamk_f32 v58, v58, 0x3c2aaaab, v206
	v_cmp_gt_f32_e32 vcc, s30, v58
	v_mul_f32_e32 v59, 0x4b800000, v58
	s_nop 0
	v_cndmask_b32_e32 v58, v58, v59, vcc
	v_rsq_f32_e32 v58, v58
	s_nop 0
	v_mul_f32_e32 v59, 0x45800000, v58
	v_cndmask_b32_e32 v58, v58, v59, vcc
	s_waitcnt vmcnt(6)
	v_pk_mul_f32 v[14:15], v[14:15], v[58:59] op_sel_hi:[1,0]
	v_pk_mul_f32 v[16:17], v[16:17], v[58:59] op_sel_hi:[1,0]
	v_pk_mul_f32 v[14:15], v[36:37], v[14:15]
	v_pk_mul_f32 v[16:17], v[38:39], v[16:17]
	v_pk_mul_f32 v[36:37], v[64:65], v[58:59] op_sel_hi:[1,0]
	v_pk_mul_f32 v[38:39], v[66:67], v[58:59] op_sel_hi:[1,0]
	v_pk_mul_f32 v[14:15], v[14:15], s[14:15] op_sel_hi:[1,0]
	v_pk_mul_f32 v[16:17], v[16:17], s[14:15] op_sel_hi:[1,0]
	v_pk_mul_f32 v[36:37], v[82:83], v[36:37]
	v_pk_mul_f32 v[38:39], v[78:79], v[38:39]
	v_cvt_pk_bf16_f32 v14, v14, v15
	v_cvt_pk_bf16_f32 v15, v16, v17
	v_pk_mul_f32 v[40:41], v[40:41], v[58:59] op_sel_hi:[1,0]
	v_pk_mul_f32 v[42:43], v[42:43], v[58:59] op_sel_hi:[1,0]
	global_store_dwordx2 v[18:19], v[14:15], off
	v_pk_mul_f32 v[14:15], v[36:37], s[14:15] op_sel_hi:[1,0]
	v_pk_mul_f32 v[16:17], v[38:39], s[14:15] op_sel_hi:[1,0]
	v_pk_mul_f32 v[40:41], v[90:91], v[40:41]
	v_pk_mul_f32 v[42:43], v[86:87], v[42:43]
	v_cvt_pk_bf16_f32 v14, v14, v15
	v_cvt_pk_bf16_f32 v15, v16, v17
	v_pk_mul_f32 v[44:45], v[44:45], v[58:59] op_sel_hi:[1,0]
	v_pk_mul_f32 v[46:47], v[46:47], v[58:59] op_sel_hi:[1,0]
	global_store_dwordx2 v[18:19], v[14:15], off offset:16
	v_pk_mul_f32 v[14:15], v[40:41], s[14:15] op_sel_hi:[1,0]
	v_pk_mul_f32 v[16:17], v[42:43], s[14:15] op_sel_hi:[1,0]
	v_pk_mul_f32 v[44:45], v[102:103], v[44:45]
	v_pk_mul_f32 v[46:47], v[94:95], v[46:47]
	v_cvt_pk_bf16_f32 v14, v14, v15
	v_cvt_pk_bf16_f32 v15, v16, v17
	v_pk_mul_f32 v[48:49], v[48:49], v[58:59] op_sel_hi:[1,0]
	v_pk_mul_f32 v[50:51], v[50:51], v[58:59] op_sel_hi:[1,0]
	global_store_dwordx2 v[18:19], v[14:15], off offset:32
	v_pk_mul_f32 v[14:15], v[44:45], s[14:15] op_sel_hi:[1,0]
	v_pk_mul_f32 v[16:17], v[46:47], s[14:15] op_sel_hi:[1,0]
	v_pk_mul_f32 v[48:49], v[110:111], v[48:49]
	v_pk_mul_f32 v[50:51], v[106:107], v[50:51]
	v_cvt_pk_bf16_f32 v14, v14, v15
	v_cvt_pk_bf16_f32 v15, v16, v17
	v_pk_mul_f32 v[20:21], v[20:21], v[58:59] op_sel_hi:[1,0]
	v_pk_mul_f32 v[22:23], v[22:23], v[58:59] op_sel_hi:[1,0]
	global_store_dwordx2 v[18:19], v[14:15], off offset:48
	v_pk_mul_f32 v[14:15], v[48:49], s[14:15] op_sel_hi:[1,0]
	v_pk_mul_f32 v[16:17], v[50:51], s[14:15] op_sel_hi:[1,0]
	v_pk_mul_f32 v[20:21], v[172:173], v[20:21]
	v_pk_mul_f32 v[22:23], v[132:133], v[22:23]
	v_cvt_pk_bf16_f32 v14, v14, v15
	v_cvt_pk_bf16_f32 v15, v16, v17
	s_waitcnt vmcnt(9)
	v_pk_mul_f32 v[24:25], v[24:25], v[58:59] op_sel_hi:[1,0]
	v_pk_mul_f32 v[26:27], v[26:27], v[58:59] op_sel_hi:[1,0]
	global_store_dwordx2 v[18:19], v[14:15], off offset:64
	v_pk_mul_f32 v[14:15], v[20:21], s[14:15] op_sel_hi:[1,0]
	v_pk_mul_f32 v[16:17], v[22:23], s[14:15] op_sel_hi:[1,0]
	v_pk_mul_f32 v[24:25], v[180:181], v[24:25]
	v_pk_mul_f32 v[26:27], v[176:177], v[26:27]
	s_waitcnt vmcnt(6)
	v_pk_mul_f32 v[4:5], v[4:5], v[58:59] op_sel_hi:[1,0]
	v_cvt_pk_bf16_f32 v14, v14, v15
	v_cvt_pk_bf16_f32 v15, v16, v17
	v_pk_mul_f32 v[28:29], v[28:29], v[58:59] op_sel_hi:[1,0]
	v_pk_mul_f32 v[30:31], v[30:31], v[58:59] op_sel_hi:[1,0]
	v_pk_mul_f32 v[4:5], v[8:9], v[4:5]
	v_pk_mul_f32 v[8:9], v[68:69], v[58:59] op_sel_hi:[1,0]
	v_pk_mul_f32 v[60:61], v[70:71], v[58:59] op_sel_hi:[1,0]
	global_store_dwordx2 v[18:19], v[14:15], off offset:80
	v_pk_mul_f32 v[14:15], v[24:25], s[14:15] op_sel_hi:[1,0]
	v_pk_mul_f32 v[16:17], v[26:27], s[14:15] op_sel_hi:[1,0]
	v_pk_mul_f32 v[28:29], v[188:189], v[28:29]
	v_pk_mul_f32 v[30:31], v[184:185], v[30:31]
	v_pk_mul_f32 v[32:33], v[32:33], v[58:59] op_sel_hi:[1,0]
	v_pk_mul_f32 v[34:35], v[34:35], v[58:59] op_sel_hi:[1,0]
	v_pk_mul_f32 v[8:9], v[200:201], v[8:9]
	v_pk_mul_f32 v[52:53], v[52:53], v[60:61]
	s_waitcnt vmcnt(6)
	v_pk_mul_f32 v[10:11], v[10:11], v[58:59] op_sel_hi:[1,0]
	v_pk_mul_f32 v[12:13], v[12:13], v[58:59] op_sel_hi:[1,0]
	v_cvt_pk_bf16_f32 v14, v14, v15
	v_cvt_pk_bf16_f32 v15, v16, v17
	v_pk_mul_f32 v[32:33], v[196:197], v[32:33]
	v_pk_mul_f32 v[34:35], v[192:193], v[34:35]
	v_pk_mul_f32 v[10:11], v[54:55], v[10:11]
	v_pk_mul_f32 v[12:13], v[56:57], v[12:13]
	v_pk_mul_f32 v[54:55], v[116:117], v[8:9]
	v_pk_mul_f32 v[56:57], v[120:121], v[52:53]
	global_store_dwordx2 v[18:19], v[14:15], off offset:96
	v_pk_mul_f32 v[14:15], v[28:29], s[14:15] op_sel_hi:[1,0]
	v_pk_mul_f32 v[16:17], v[30:31], s[14:15] op_sel_hi:[1,0]
	v_pk_mul_f32 v[6:7], v[6:7], v[58:59] op_sel_hi:[1,0]
	v_pk_fma_f32 v[54:55], v[118:119], v[32:33], v[54:55] neg_lo:[0,0,1] neg_hi:[0,0,1]
	v_pk_fma_f32 v[56:57], v[122:123], v[34:35], v[56:57] neg_lo:[0,0,1] neg_hi:[0,0,1]
	v_cvt_pk_bf16_f32 v14, v14, v15
	v_cvt_pk_bf16_f32 v15, v16, v17
	v_pk_mul_f32 v[6:7], v[232:233], v[6:7]
	v_pk_mul_f32 v[58:59], v[124:125], v[10:11]
	v_pk_mul_f32 v[60:61], v[150:151], v[12:13]
	global_store_dwordx2 v[18:19], v[14:15], off offset:112
	v_pk_mul_f32 v[14:15], v[54:55], s[14:15] op_sel_hi:[1,0]
	v_pk_mul_f32 v[16:17], v[56:57], s[14:15] op_sel_hi:[1,0]
	v_pk_fma_f32 v[58:59], v[126:127], v[4:5], v[58:59] neg_lo:[0,0,1] neg_hi:[0,0,1]
	v_pk_fma_f32 v[60:61], v[152:153], v[6:7], v[60:61] neg_lo:[0,0,1] neg_hi:[0,0,1]
	v_cvt_pk_bf16_f32 v14, v14, v15
	v_cvt_pk_bf16_f32 v15, v16, v17
	global_store_dwordx2 v[18:19], v[14:15], off offset:128
	v_pk_mul_f32 v[14:15], v[58:59], s[14:15] op_sel_hi:[1,0]
	v_pk_mul_f32 v[16:17], v[60:61], s[14:15] op_sel_hi:[1,0]
	v_cvt_pk_bf16_f32 v14, v14, v15
	v_cvt_pk_bf16_f32 v15, v16, v17
	global_store_dwordx2 v[18:19], v[14:15], off offset:144
	v_pk_mul_f32 v[14:15], v[116:117], v[32:33]
	v_pk_mul_f32 v[4:5], v[124:125], v[4:5]
	v_pk_mul_f32 v[6:7], v[150:151], v[6:7]
	v_pk_fma_f32 v[8:9], v[118:119], v[8:9], v[14:15]
	v_pk_mul_f32 v[14:15], v[120:121], v[34:35]
	v_pk_fma_f32 v[4:5], v[126:127], v[10:11], v[4:5]
	v_pk_fma_f32 v[6:7], v[152:153], v[12:13], v[6:7]
	v_pk_fma_f32 v[14:15], v[122:123], v[52:53], v[14:15]
	v_pk_mul_f32 v[4:5], v[4:5], s[14:15] op_sel_hi:[1,0]
	v_pk_mul_f32 v[6:7], v[6:7], s[14:15] op_sel_hi:[1,0]
	v_pk_mul_f32 v[8:9], v[8:9], s[14:15] op_sel_hi:[1,0]
	v_pk_mul_f32 v[14:15], v[14:15], s[14:15] op_sel_hi:[1,0]
	v_cvt_pk_bf16_f32 v4, v4, v5
	v_cvt_pk_bf16_f32 v5, v6, v7
	v_readlane_b32 s14, v255, 3
	v_cvt_pk_bf16_f32 v8, v8, v9
	v_cvt_pk_bf16_f32 v9, v14, v15
	global_store_dwordx2 v[18:19], v[4:5], off offset:176
	s_add_u32 s18, s14, s5
	v_readlane_b32 s5, v255, 4
	v_ashrrev_i32_e32 v4, 4, v159
	global_store_dwordx2 v[18:19], v[8:9], off offset:160
	s_addc_u32 s19, s5, 0
	v_and_b32_e32 v8, 0xf0, v162
	v_mov_b32_e32 v9, v3
	v_ashrrev_i32_e32 v5, 31, v4
	v_lshl_add_u64 v[10:11], s[18:19], 0, v[8:9]
	v_lshlrev_b64 v[6:7], 8, v[4:5]
	v_lshl_add_u64 v[6:7], v[10:11], 0, v[6:7]
	s_movk_i32 s5, 0x110
	s_barrier
; DI float bflo(uint32_t u) { return __uint_as_float(u << 16); }
; DI float bfhi(uint32_t u) { return __uint_as_float(u & 0xffff0000u); }
; DI void prep_item(const Params& p, int layer, int item, char* smem) {
;     ...
;   {
;     const u16* src = WUKV + (size_t)(hd * 128) * 128;
; #pragma unroll
;     for (int i = 0; i < 8; ++i) {
;       const int idx = tid + 256 * i, row = idx >> 4, c = idx & 15;
;       *(uint4*)&sWk[row][c * 8] = *(const uint4*)(src + (size_t)row * 128 + c * 8);
;     }
;   }
;   __syncthreads();
;   {
;     bf16x8 bk[8];
;     float ss = 0.f;
; #pragma unroll
;     for (int ks = 0; ks < 8; ++ks) {
;       uint4 u = *(const uint4*)(prow + O_CKV + ks * 16 + 8 * h);
;       bk[ks] = __builtin_bit_cast(bf16x8, u);
;       float f;
;       f = bflo(u.x); ss += f * f; f = bfhi(u.x); ss += f * f; f = bflo(u.y); ss += f * f; f = bfhi(u.y); ss += f * f;
;       f = bflo(u.z); ss += f * f; f = bfhi(u.z); ss += f * f; f = bflo(u.w); ss += f * f; f = bfhi(u.w); ss += f * f;
;     }
	v_mad_u64_u32 v[12:13], s[18:19], v4, s5, v[8:9]
	global_load_dwordx4 v[40:43], v[6:7], off
	v_mad_u32_u24 v101, v161, s5, v154
	s_lshl_b32 s16, s1, 7
	s_cmp_lt_i32 s1, 1
	v_ashrrev_i32_e32 v4, 4, v163
	v_ashrrev_i32_e32 v5, 31, v4
	v_lshlrev_b64 v[6:7], 8, v[4:5]
	v_lshl_add_u64 v[6:7], v[10:11], 0, v[6:7]
	global_load_dwordx4 v[44:47], v[6:7], off
	v_ashrrev_i32_e32 v4, 4, v164
	v_ashrrev_i32_e32 v5, 31, v4
	v_lshlrev_b64 v[6:7], 8, v[4:5]
	v_lshl_add_u64 v[6:7], v[10:11], 0, v[6:7]
	global_load_dwordx4 v[48:51], v[6:7], off
	v_ashrrev_i32_e32 v4, 4, v165
	v_ashrrev_i32_e32 v5, 31, v4
	v_lshlrev_b64 v[6:7], 8, v[4:5]
	v_lshl_add_u64 v[6:7], v[10:11], 0, v[6:7]
	global_load_dwordx4 v[52:55], v[6:7], off
	v_ashrrev_i32_e32 v4, 4, v166
	v_ashrrev_i32_e32 v5, 31, v4
	v_lshlrev_b64 v[6:7], 8, v[4:5]
	v_lshl_add_u64 v[6:7], v[10:11], 0, v[6:7]
	global_load_dwordx4 v[56:59], v[6:7], off
	v_ashrrev_i32_e32 v4, 4, v167
	v_ashrrev_i32_e32 v5, 31, v4
	v_lshlrev_b64 v[6:7], 8, v[4:5]
	v_lshl_add_u64 v[6:7], v[10:11], 0, v[6:7]
	global_load_dwordx4 v[60:63], v[6:7], off
	v_ashrrev_i32_e32 v4, 4, v168
	v_ashrrev_i32_e32 v5, 31, v4
	v_lshlrev_b64 v[6:7], 8, v[4:5]
	v_lshl_add_u64 v[6:7], v[10:11], 0, v[6:7]
	global_load_dwordx4 v[64:67], v[6:7], off
	v_ashrrev_i32_e32 v4, 4, v169
	v_ashrrev_i32_e32 v5, 31, v4
	v_lshlrev_b64 v[6:7], 8, v[4:5]
	v_lshl_add_u64 v[6:7], v[10:11], 0, v[6:7]
	global_load_dwordx4 v[68:71], v[6:7], off
	v_readlane_b32 s18, v252, 10
	v_readlane_b32 s19, v252, 11
	s_mov_b32 s5, 0x80000
	s_waitcnt vmcnt(7)
	ds_write_b128 v12, v[40:43]
	s_waitcnt vmcnt(6)
	ds_write_b128 v12, v[44:47] offset:4352
	s_waitcnt vmcnt(5)
	ds_write_b128 v12, v[48:51] offset:8704
	s_waitcnt vmcnt(4)
	ds_write_b128 v12, v[52:55] offset:13056
	s_waitcnt vmcnt(3)
	ds_write_b128 v12, v[56:59] offset:17408
	s_waitcnt vmcnt(2)
	ds_write_b128 v12, v[60:63] offset:21760
	s_waitcnt vmcnt(1)
	ds_write_b128 v12, v[64:67] offset:26112
	s_waitcnt vmcnt(0)
	ds_write_b128 v12, v[68:71] offset:30464
	s_waitcnt lgkmcnt(0)
	s_barrier
	global_load_dwordx4 v[36:39], v[156:157], off offset:512
	global_load_dwordx4 v[92:95], v[156:157], off offset:544
	global_load_dwordx4 v[88:91], v[156:157], off offset:576
	global_load_dwordx4 v[84:87], v[156:157], off offset:608
	global_load_dwordx4 v[80:83], v[156:157], off offset:640
	global_load_dwordx4 v[68:71], v[156:157], off offset:672
	global_load_dwordx4 v[72:75], v[156:157], off offset:704
	global_load_dwordx4 v[76:79], v[156:157], off offset:736
	s_waitcnt vmcnt(7)
	v_lshlrev_b32_e32 v4, 16, v36
	v_mul_f32_e32 v6, v4, v4
	v_and_b32_e32 v4, 0xffff0000, v36
	v_fmac_f32_e32 v6, v4, v4
	v_lshlrev_b32_e32 v4, 16, v37
	v_fmac_f32_e32 v6, v4, v4
	v_and_b32_e32 v4, 0xffff0000, v37
	v_fmac_f32_e32 v6, v4, v4
	v_lshlrev_b32_e32 v4, 16, v38
	v_fmac_f32_e32 v6, v4, v4
	v_and_b32_e32 v4, 0xffff0000, v38
	v_fmac_f32_e32 v6, v4, v4
	v_lshlrev_b32_e32 v4, 16, v39
	v_fmac_f32_e32 v6, v4, v4
	v_and_b32_e32 v4, 0xffff0000, v39
	v_fmac_f32_e32 v6, v4, v4
	s_waitcnt vmcnt(6)
	v_lshlrev_b32_e32 v4, 16, v92
	v_fmac_f32_e32 v6, v4, v4
	v_and_b32_e32 v4, 0xffff0000, v92
	v_fmac_f32_e32 v6, v4, v4
	v_lshlrev_b32_e32 v4, 16, v93
	v_fmac_f32_e32 v6, v4, v4
	v_and_b32_e32 v4, 0xffff0000, v93
	v_fmac_f32_e32 v6, v4, v4
	v_lshlrev_b32_e32 v4, 16, v94
	v_fmac_f32_e32 v6, v4, v4
	v_and_b32_e32 v4, 0xffff0000, v94
	v_fmac_f32_e32 v6, v4, v4
	v_lshlrev_b32_e32 v4, 16, v95
	v_fmac_f32_e32 v6, v4, v4
	v_and_b32_e32 v4, 0xffff0000, v95
	v_fmac_f32_e32 v6, v4, v4
	s_waitcnt vmcnt(5)
	v_lshlrev_b32_e32 v4, 16, v88
	v_fmac_f32_e32 v6, v4, v4
	v_and_b32_e32 v4, 0xffff0000, v88
	v_fmac_f32_e32 v6, v4, v4
	v_lshlrev_b32_e32 v4, 16, v89
	v_fmac_f32_e32 v6, v4, v4
	v_and_b32_e32 v4, 0xffff0000, v89
	v_fmac_f32_e32 v6, v4, v4
	v_lshlrev_b32_e32 v4, 16, v90
	v_fmac_f32_e32 v6, v4, v4
	v_and_b32_e32 v4, 0xffff0000, v90
	v_fmac_f32_e32 v6, v4, v4
	v_lshlrev_b32_e32 v4, 16, v91
	v_fmac_f32_e32 v6, v4, v4
	v_and_b32_e32 v4, 0xffff0000, v91
	v_fmac_f32_e32 v6, v4, v4
	s_waitcnt vmcnt(4)
	v_lshlrev_b32_e32 v4, 16, v84
	v_fmac_f32_e32 v6, v4, v4
	v_and_b32_e32 v4, 0xffff0000, v84
	v_fmac_f32_e32 v6, v4, v4
	v_lshlrev_b32_e32 v4, 16, v85
	v_fmac_f32_e32 v6, v4, v4
	v_and_b32_e32 v4, 0xffff0000, v85
	v_fmac_f32_e32 v6, v4, v4
	v_lshlrev_b32_e32 v4, 16, v86
	v_fmac_f32_e32 v6, v4, v4
	v_and_b32_e32 v4, 0xffff0000, v86
	v_fmac_f32_e32 v6, v4, v4
	v_lshlrev_b32_e32 v4, 16, v87
	v_fmac_f32_e32 v6, v4, v4
	v_and_b32_e32 v4, 0xffff0000, v87
	v_fmac_f32_e32 v6, v4, v4
	s_waitcnt vmcnt(3)
	v_lshlrev_b32_e32 v4, 16, v80
	v_fmac_f32_e32 v6, v4, v4
	v_and_b32_e32 v4, 0xffff0000, v80
	v_fmac_f32_e32 v6, v4, v4
	v_lshlrev_b32_e32 v4, 16, v81
	v_fmac_f32_e32 v6, v4, v4
	v_and_b32_e32 v4, 0xffff0000, v81
	v_fmac_f32_e32 v6, v4, v4
	v_lshlrev_b32_e32 v4, 16, v82
	v_fmac_f32_e32 v6, v4, v4
	v_and_b32_e32 v4, 0xffff0000, v82
	v_fmac_f32_e32 v6, v4, v4
	v_lshlrev_b32_e32 v4, 16, v83
	v_fmac_f32_e32 v6, v4, v4
	v_and_b32_e32 v4, 0xffff0000, v83
	v_fmac_f32_e32 v6, v4, v4
	s_waitcnt vmcnt(2)
	v_lshlrev_b32_e32 v4, 16, v68
	v_fmac_f32_e32 v6, v4, v4
	v_and_b32_e32 v4, 0xffff0000, v68
	v_fmac_f32_e32 v6, v4, v4
	v_lshlrev_b32_e32 v4, 16, v69
	v_fmac_f32_e32 v6, v4, v4
	v_and_b32_e32 v4, 0xffff0000, v69
	v_fmac_f32_e32 v6, v4, v4
	v_lshlrev_b32_e32 v4, 16, v70
	v_fmac_f32_e32 v6, v4, v4
	v_and_b32_e32 v4, 0xffff0000, v70
	v_fmac_f32_e32 v6, v4, v4
	v_lshlrev_b32_e32 v4, 16, v71
	v_fmac_f32_e32 v6, v4, v4
	v_and_b32_e32 v4, 0xffff0000, v71
	v_fmac_f32_e32 v6, v4, v4
	s_waitcnt vmcnt(1)
; #define MFMA32(a, b, c) __builtin_amdgcn_mfma_f32_32x32x16_bf16((a), (b), (c), 0, 0, 0)
; DI float bflo(uint32_t u) { return __uint_as_float(u << 16); }
; DI float bfhi(uint32_t u) { return __uint_as_float(u & 0xffff0000u); }
; DI float xor32(float v) { return __shfl_xor(v, 32); }
; DI f32x16 zero16() { f32x16 z; _Pragma("unroll") for (int i = 0; i < 16; ++i) z[i] = 0.f; return z; }
; DI void prep_item(const Params& p, int layer, int item, char* smem) {
;     ...
;     for (int ks = 0; ks < 8; ++ks) {
;       uint4 u = *(const uint4*)(prow + O_CKV + ks * 16 + 8 * h);
;       bk[ks] = __builtin_bit_cast(bf16x8, u);
;       float f;
;       f = bflo(u.x); ss += f * f; f = bfhi(u.x); ss += f * f; f = bflo(u.y); ss += f * f; f = bfhi(u.y); ss += f * f;
;       f = bflo(u.z); ss += f * f; f = bfhi(u.z); ss += f * f; f = bflo(u.w); ss += f * f; f = bfhi(u.w); ss += f * f;
;     }
;     ss += xor32(ss);
;     const float rkv = rsqrtf(ss * (1.f / 128.f) + EPS);
;     f32x16 acc[4];
;     acc[0] = zero16(); acc[1] = zero16(); acc[2] = zero16(); acc[3] = zero16();
; #pragma unroll
;     for (int ks = 0; ks < 8; ++ks) {
; #pragma unroll
;       for (int nt = 0; nt < 4; ++nt) {
;         bf16x8 a = *(const bf16x8*)&sWk[nt * 32 + r][ks * 16 + 8 * h];
;         acc[nt] = MFMA32(a, bk[ks], acc[nt]);
;       }
;     }
	v_lshlrev_b32_e32 v4, 16, v72
	v_fmac_f32_e32 v6, v4, v4
	v_and_b32_e32 v4, 0xffff0000, v72
	v_fmac_f32_e32 v6, v4, v4
	v_lshlrev_b32_e32 v4, 16, v73
	v_fmac_f32_e32 v6, v4, v4
	v_and_b32_e32 v4, 0xffff0000, v73
	v_fmac_f32_e32 v6, v4, v4
	v_lshlrev_b32_e32 v4, 16, v74
	v_fmac_f32_e32 v6, v4, v4
	v_and_b32_e32 v4, 0xffff0000, v74
	v_fmac_f32_e32 v6, v4, v4
	v_and_b32_e32 v4, 0xffff0000, v75
	v_lshlrev_b32_e32 v5, 16, v75
	v_pk_mul_f32 v[4:5], v[4:5], v[4:5]
	s_nop 0
	v_add_f32_e32 v5, v5, v6
	v_add_f32_e32 v6, v4, v5
	s_waitcnt vmcnt(0)
	v_and_b32_e32 v4, 0xffff0000, v76
	v_lshlrev_b32_e32 v5, 16, v76
	v_pk_mul_f32 v[4:5], v[4:5], v[4:5]
	s_nop 0
	v_add_f32_e32 v5, v5, v6
	v_add_f32_e32 v6, v4, v5
	v_and_b32_e32 v4, 0xffff0000, v77
	v_lshlrev_b32_e32 v5, 16, v77
	v_pk_mul_f32 v[4:5], v[4:5], v[4:5]
	s_nop 0
	v_add_f32_e32 v5, v5, v6
	v_add_f32_e32 v6, v4, v5
	v_and_b32_e32 v4, 0xffff0000, v78
	v_lshlrev_b32_e32 v5, 16, v78
	v_pk_mul_f32 v[4:5], v[4:5], v[4:5]
	s_nop 0
	v_add_f32_e32 v5, v5, v6
	v_add_f32_e32 v6, v4, v5
	v_and_b32_e32 v4, 0xffff0000, v79
	v_lshlrev_b32_e32 v5, 16, v79
	v_pk_mul_f32 v[4:5], v[4:5], v[4:5]
	s_nop 0
	v_add_f32_e32 v5, v5, v6
	v_add_f32_e32 v4, v4, v5
	ds_bpermute_b32 v5, v155, v4
	s_waitcnt lgkmcnt(0)
	v_add_f32_e32 v4, v4, v5
	v_fmamk_f32 v4, v4, 0x3c000000, v206
	v_cmp_gt_f32_e32 vcc, s30, v4
	v_mul_f32_e32 v5, 0x4b800000, v4
	s_nop 0
	v_cndmask_b32_e32 v4, v4, v5, vcc
	v_rsq_f32_e32 v99, v4
	ds_read_b128 v[4:7], v101
	ds_read_b128 v[102:105], v101 offset:32
	s_waitcnt lgkmcnt(1)
	v_mfma_f32_32x32x16_bf16 v[20:35], v[4:7], v[36:39], 0
	ds_read_b128 v[4:7], v101 offset:8704
	ds_read_b128 v[40:43], v101 offset:17408
	v_mul_f32_e32 v100, 0x45800000, v99
	global_load_dwordx4 v[162:165], v154, s[10:11] offset:256
	global_load_dwordx4 v[166:169], v154, s[10:11] offset:320
	global_load_dwordx4 v[170:173], v154, s[10:11] offset:32
	global_load_dwordx4 v[174:177], v154, s[10:11] offset:160
	s_waitcnt lgkmcnt(2)
	v_mfma_f32_32x32x16_bf16 v[20:35], v[102:105], v[92:95], v[20:35]
	ds_read_b128 v[102:105], v101 offset:8736
	s_waitcnt lgkmcnt(2)
	v_mfma_f32_32x32x16_bf16 v[4:19], v[4:7], v[36:39], 0
	s_waitcnt lgkmcnt(0)
	v_mfma_f32_32x32x16_bf16 v[4:19], v[102:105], v[92:95], v[4:19]
	ds_read_b128 v[102:105], v101 offset:17440
	v_mfma_f32_32x32x16_bf16 v[52:67], v[40:43], v[36:39], 0
	ds_read_b128 v[40:43], v101 offset:26112
	s_waitcnt lgkmcnt(1)
	v_mfma_f32_32x32x16_bf16 v[52:67], v[102:105], v[92:95], v[52:67]
	ds_read_b128 v[102:105], v101 offset:26144
	s_waitcnt lgkmcnt(1)
	v_mfma_f32_32x32x16_bf16 v[36:51], v[40:43], v[36:39], 0
	s_waitcnt lgkmcnt(0)
	v_mfma_f32_32x32x16_bf16 v[36:51], v[102:105], v[92:95], v[36:51]
	ds_read_b128 v[92:95], v101 offset:64
	s_waitcnt lgkmcnt(0)
	v_mfma_f32_32x32x16_bf16 v[20:35], v[92:95], v[88:91], v[20:35]
	ds_read_b128 v[92:95], v101 offset:8768
	s_waitcnt lgkmcnt(0)
	v_mfma_f32_32x32x16_bf16 v[4:19], v[92:95], v[88:91], v[4:19]
	ds_read_b128 v[92:95], v101 offset:17472
	s_waitcnt lgkmcnt(0)
	v_mfma_f32_32x32x16_bf16 v[52:67], v[92:95], v[88:91], v[52:67]
	ds_read_b128 v[92:95], v101 offset:26176
	s_waitcnt lgkmcnt(0)
	v_mfma_f32_32x32x16_bf16 v[36:51], v[92:95], v[88:91], v[36:51]
	ds_read_b128 v[88:91], v101 offset:96
	s_waitcnt lgkmcnt(0)
	v_mfma_f32_32x32x16_bf16 v[20:35], v[88:91], v[84:87], v[20:35]
	ds_read_b128 v[88:91], v101 offset:8800
	s_waitcnt lgkmcnt(0)
	v_mfma_f32_32x32x16_bf16 v[4:19], v[88:91], v[84:87], v[4:19]
	ds_read_b128 v[88:91], v101 offset:17504
	s_waitcnt lgkmcnt(0)
	v_mfma_f32_32x32x16_bf16 v[52:67], v[88:91], v[84:87], v[52:67]
	ds_read_b128 v[88:91], v101 offset:26208
	s_waitcnt lgkmcnt(0)
	v_mfma_f32_32x32x16_bf16 v[36:51], v[88:91], v[84:87], v[36:51]
	ds_read_b128 v[84:87], v101 offset:128
	s_waitcnt lgkmcnt(0)
	v_mfma_f32_32x32x16_bf16 v[20:35], v[84:87], v[80:83], v[20:35]
	ds_read_b128 v[84:87], v101 offset:8832
	s_waitcnt lgkmcnt(0)
	v_mfma_f32_32x32x16_bf16 v[4:19], v[84:87], v[80:83], v[4:19]
	ds_read_b128 v[84:87], v101 offset:17536
	s_waitcnt lgkmcnt(0)
	v_mfma_f32_32x32x16_bf16 v[52:67], v[84:87], v[80:83], v[52:67]
	ds_read_b128 v[84:87], v101 offset:26240
	s_waitcnt lgkmcnt(0)
	v_mfma_f32_32x32x16_bf16 v[36:51], v[84:87], v[80:83], v[36:51]
	ds_read_b128 v[80:83], v101 offset:160
	v_cndmask_b32_e32 v84, v99, v100, vcc
	s_waitcnt lgkmcnt(0)
	v_mfma_f32_32x32x16_bf16 v[20:35], v[80:83], v[68:71], v[20:35]
	ds_read_b128 v[80:83], v101 offset:8864
	s_waitcnt lgkmcnt(0)
	v_mfma_f32_32x32x16_bf16 v[4:19], v[80:83], v[68:71], v[4:19]
	ds_read_b128 v[80:83], v101 offset:17568
	s_waitcnt lgkmcnt(0)
	v_mfma_f32_32x32x16_bf16 v[52:67], v[80:83], v[68:71], v[52:67]
	ds_read_b128 v[80:83], v101 offset:26272
	s_waitcnt lgkmcnt(0)
	v_mfma_f32_32x32x16_bf16 v[36:51], v[80:83], v[68:71], v[36:51]
	ds_read_b128 v[68:71], v101 offset:192
	s_waitcnt lgkmcnt(0)
	v_mfma_f32_32x32x16_bf16 v[20:35], v[68:71], v[72:75], v[20:35]
	ds_read_b128 v[68:71], v101 offset:8896
	s_waitcnt lgkmcnt(0)
	v_mfma_f32_32x32x16_bf16 v[4:19], v[68:71], v[72:75], v[4:19]
	ds_read_b128 v[68:71], v101 offset:17600
	s_waitcnt lgkmcnt(0)
	v_mfma_f32_32x32x16_bf16 v[52:67], v[68:71], v[72:75], v[52:67]
	ds_read_b128 v[68:71], v101 offset:26304
	s_waitcnt lgkmcnt(0)
	v_mfma_f32_32x32x16_bf16 v[36:51], v[68:71], v[72:75], v[36:51]
	ds_read_b128 v[68:71], v101 offset:224
	s_waitcnt lgkmcnt(0)
	v_mfma_f32_32x32x16_bf16 v[20:35], v[68:71], v[76:79], v[20:35]
	ds_read_b128 v[68:71], v101 offset:8928
	s_waitcnt lgkmcnt(0)
	v_mfma_f32_32x32x16_bf16 v[4:19], v[68:71], v[76:79], v[4:19]
	ds_read_b128 v[68:71], v101 offset:17632
	s_waitcnt lgkmcnt(0)
; DI float bflo(uint32_t u) { return __uint_as_float(u << 16); }
; DI float bfhi(uint32_t u) { return __uint_as_float(u & 0xffff0000u); }
; DI float xor32(float v) { return __shfl_xor(v, 32); }
; DI void prep_item(const Params& p, int layer, int item, char* smem) {
;     ...
;     float kpe[16];
; #pragma unroll
;     for (int g = 0; g < 4; ++g) {
;       uint2 u = *(const uint2*)(prow + O_KPE + 8 * g + 4 * h);
;       kpe[4 * g] = bflo(u.x); kpe[4 * g + 1] = bfhi(u.x); kpe[4 * g + 2] = bflo(u.y); kpe[4 * g + 3] = bfhi(u.y);
;     }
;     float ss2 = 0.f;
; #pragma unroll
;     for (int nt = 0; nt < 4; ++nt)
; #pragma unroll
;       for (int i = 0; i < 16; ++i) acc[nt][i] *= rkv;
; #pragma unroll
;     for (int i = 0; i < 16; ++i) ss2 += acc[0][i] * acc[0][i] + acc[1][i] * acc[1][i] + kpe[i] * kpe[i];
;     ss2 += xor32(ss2);
;     const float r2 = rsqrtf(ss2 * (1.f / 96.f) + EPS);
;     const float* gk = p.mla_k_g + layer * 96;
; #pragma unroll
;     for (int g = 0; g < 4; ++g) {
;       float4 g0 = *(const float4*)(gk + 8 * g + 4 * h);
;       float4 g1 = *(const float4*)(gk + 32 + 8 * g + 4 * h);
;       float4 g2 = *(const float4*)(gk + 64 + 8 * g + 4 * h);
;       acc[0][4 * g] *= r2 * g0.x; acc[0][4 * g + 1] *= r2 * g0.y; acc[0][4 * g + 2] *= r2 * g0.z; acc[0][4 * g + 3] *= r2 * g0.w;
;       acc[1][4 * g] *= r2 * g1.x; acc[1][4 * g + 1] *= r2 * g1.y; acc[1][4 * g + 2] *= r2 * g1.z; acc[1][4 * g + 3] *= r2 * g1.w;
;       kpe[4 * g] *= r2 * g2.x; kpe[4 * g + 1] *= r2 * g2.y; kpe[4 * g + 2] *= r2 * g2.z; kpe[4 * g + 3] *= r2 * g2.w;
	v_mfma_f32_32x32x16_bf16 v[52:67], v[68:71], v[76:79], v[52:67]
	ds_read_b128 v[68:71], v101 offset:26336
	s_waitcnt lgkmcnt(0)
	v_mfma_f32_32x32x16_bf16 v[36:51], v[68:71], v[76:79], v[36:51]
	v_lshl_add_u64 v[68:69], v[114:115], 0, v[2:3]
	global_load_dwordx2 v[70:71], v[68:69], off offset:2560
	s_nop 6
	v_mul_f32_e32 v106, v54, v84
	v_mul_f32_e32 v105, v55, v84
	v_mul_f32_e32 v104, v56, v84
	v_mul_f32_e32 v103, v57, v84
	v_mul_f32_e32 v99, v61, v84
	v_mul_f32_e32 v85, v40, v84
	v_pk_mul_f32 v[54:55], v[14:15], v[84:85] op_sel_hi:[1,0]
	v_pk_mul_f32 v[56:57], v[30:31], v[84:85] op_sel_hi:[1,0]
	v_pk_mul_f32 v[14:15], v[54:55], v[54:55]
	v_pk_mul_f32 v[30:31], v[16:17], v[84:85] op_sel_hi:[1,0]
	v_pk_fma_f32 v[14:15], v[56:57], v[56:57], v[14:15]
	v_mul_f32_e32 v95, v62, v84
	v_mul_f32_e32 v89, v36, v84
	v_mul_f32_e32 v88, v37, v84
	v_mul_f32_e32 v62, v46, v84
	v_mul_f32_e32 v61, v47, v84
	v_pk_mul_f32 v[46:47], v[32:33], v[84:85] op_sel_hi:[1,0]
	v_pk_mul_f32 v[18:19], v[18:19], v[84:85] op_sel_hi:[1,0]
	v_mul_f32_e32 v102, v58, v84
	v_mul_f32_e32 v90, v67, v84
	v_mul_f32_e32 v67, v41, v84
	v_mul_f32_e32 v58, v50, v84
	v_mul_f32_e32 v41, v51, v84
	v_pk_mul_f32 v[50:51], v[34:35], v[84:85] op_sel_hi:[1,0]
	v_mul_f32_e32 v94, v63, v84
	v_mul_f32_e32 v93, v64, v84
	v_mul_f32_e32 v92, v65, v84
	v_mul_f32_e32 v91, v66, v84
	v_mul_f32_e32 v66, v42, v84
	v_mul_f32_e32 v65, v43, v84
	v_mul_f32_e32 v64, v44, v84
	v_mul_f32_e32 v63, v45, v84
	global_load_dwordx4 v[42:45], v154, s[10:11] offset:128
	v_mul_f32_e32 v101, v59, v84
	v_mul_f32_e32 v100, v60, v84
	v_mul_f32_e32 v60, v48, v84
	v_mul_f32_e32 v59, v49, v84
	v_pk_mul_f32 v[48:49], v[4:5], v[84:85] op_sel_hi:[1,0]
	v_mul_f32_e32 v87, v38, v84
	v_mul_f32_e32 v86, v39, v84
	v_pk_mul_f32 v[38:39], v[20:21], v[84:85] op_sel_hi:[1,0]
	v_pk_mul_f32 v[20:21], v[6:7], v[84:85] op_sel_hi:[1,0]
	v_pk_mul_f32 v[4:5], v[48:49], v[48:49]
	v_pk_mul_f32 v[22:23], v[22:23], v[84:85] op_sel_hi:[1,0]
	v_pk_mul_f32 v[6:7], v[20:21], v[20:21]
	v_pk_fma_f32 v[4:5], v[38:39], v[38:39], v[4:5]
	v_pk_mul_f32 v[130:131], v[10:11], v[84:85] op_sel_hi:[1,0]
	v_pk_mul_f32 v[132:133], v[8:9], v[84:85] op_sel_hi:[1,0]
	v_pk_fma_f32 v[6:7], v[22:23], v[22:23], v[6:7]
	v_pk_mul_f32 v[26:27], v[26:27], v[84:85] op_sel_hi:[1,0]
	v_pk_mul_f32 v[24:25], v[24:25], v[84:85] op_sel_hi:[1,0]
	v_pk_mul_f32 v[178:179], v[130:131], v[130:131]
	v_mul_f32_e32 v108, v52, v84
	v_mul_f32_e32 v107, v53, v84
	v_pk_fma_f32 v[178:179], v[26:27], v[26:27], v[178:179]
	v_pk_mul_f32 v[12:13], v[12:13], v[84:85] op_sel_hi:[1,0]
	v_pk_mul_f32 v[188:189], v[28:29], v[84:85] op_sel_hi:[1,0]
	v_pk_mul_f32 v[28:29], v[12:13], v[12:13]
	s_waitcnt vmcnt(1)
	v_lshlrev_b32_e32 v72, 16, v70
	v_and_b32_e32 v73, 0xffff0000, v70
	v_lshlrev_b32_e32 v74, 16, v71
	v_and_b32_e32 v75, 0xffff0000, v71
	global_load_dwordx2 v[70:71], v[68:69], off offset:2576
	v_pk_fma_f32 v[110:111], v[72:73], v[72:73], v[4:5]
	v_pk_mul_f32 v[4:5], v[132:133], v[132:133]
	v_pk_fma_f32 v[52:53], v[74:75], v[74:75], v[6:7]
	v_pk_fma_f32 v[156:157], v[24:25], v[24:25], v[4:5]
	v_add_f32_e32 v40, v110, v111
	v_add_f32_e32 v40, v52, v40
	v_add_f32_e32 v40, v53, v40
	v_pk_fma_f32 v[28:29], v[188:189], v[188:189], v[28:29]
	s_waitcnt vmcnt(0)
	v_lshlrev_b32_e32 v76, 16, v70
	v_and_b32_e32 v77, 0xffff0000, v70
	v_lshlrev_b32_e32 v78, 16, v71
	v_and_b32_e32 v79, 0xffff0000, v71
	global_load_dwordx2 v[70:71], v[68:69], off offset:2592
	v_pk_fma_f32 v[186:187], v[78:79], v[78:79], v[178:179]
	global_load_dwordx2 v[68:69], v[68:69], off offset:2608
	v_pk_fma_f32 v[156:157], v[76:77], v[76:77], v[156:157]
	s_waitcnt vmcnt(1)
	v_lshlrev_b32_e32 v82, 16, v71
	v_and_b32_e32 v83, 0xffff0000, v71
	v_pk_fma_f32 v[36:37], v[82:83], v[82:83], v[14:15]
	v_pk_mul_f32 v[14:15], v[30:31], v[30:31]
	v_lshlrev_b32_e32 v80, 16, v70
	v_and_b32_e32 v81, 0xffff0000, v70
	s_waitcnt vmcnt(0)
	v_lshlrev_b32_e32 v70, 16, v68
	v_and_b32_e32 v71, 0xffff0000, v68
	v_pk_fma_f32 v[14:15], v[46:47], v[46:47], v[14:15]
	v_lshlrev_b32_e32 v68, 16, v69
	v_pk_fma_f32 v[32:33], v[70:71], v[70:71], v[14:15]
	v_pk_mul_f32 v[14:15], v[18:19], v[18:19]
	v_and_b32_e32 v69, 0xffff0000, v69
	v_pk_fma_f32 v[14:15], v[50:51], v[50:51], v[14:15]
	v_add_f32_e32 v40, v156, v40
	v_pk_fma_f32 v[34:35], v[68:69], v[68:69], v[14:15]
	global_load_dwordx4 v[14:17], v154, s[10:11]
	global_load_dwordx4 v[8:11], v154, s[10:11] offset:288
	global_load_dwordx4 v[4:7], v154, s[10:11] offset:352
	global_load_dwordx4 v[178:181], v154, s[10:11] offset:64
	global_load_dwordx4 v[182:185], v154, s[10:11] offset:192
	v_add_f32_e32 v40, v157, v40
	v_add_f32_e32 v40, v186, v40
	v_pk_fma_f32 v[28:29], v[80:81], v[80:81], v[28:29]
	v_add_f32_e32 v40, v187, v40
	v_add_f32_e32 v28, v28, v40
	v_add_f32_e32 v28, v29, v28
	v_add_f32_e32 v28, v36, v28
	v_add_f32_e32 v28, v37, v28
	v_add_f32_e32 v28, v32, v28
	v_add_f32_e32 v28, v33, v28
	v_add_f32_e32 v28, v34, v28
	v_add_f32_e32 v28, v35, v28
	ds_bpermute_b32 v29, v155, v28
	s_waitcnt lgkmcnt(0)
	v_add_f32_e32 v28, v28, v29
	v_fmamk_f32 v28, v28, 0x3c2aaaab, v206
	v_cmp_gt_f32_e32 vcc, s30, v28
	v_mul_f32_e32 v29, 0x4b800000, v28
	s_nop 0
	v_cndmask_b32_e32 v28, v28, v29, vcc
	v_rsq_f32_e32 v28, v28
	s_nop 0
	v_mul_f32_e32 v29, 0x45800000, v28
	v_cndmask_b32_e32 v40, v28, v29, vcc
	s_waitcnt vmcnt(4)
	v_pk_mul_f32 v[14:15], v[14:15], v[40:41] op_sel_hi:[1,0]
	s_nop 0
	v_pk_mul_f32 v[34:35], v[38:39], v[14:15]
	v_pk_mul_f32 v[14:15], v[16:17], v[40:41] op_sel_hi:[1,0]
	s_waitcnt vmcnt(3)
; DI uint32_t pack2(float a, float b) { f2_t v = {a, b}; bf2_t r = __builtin_convertvector(v, bf2_t); return __builtin_bit_cast(uint32_t, r); }
; DI u16 f2bf(float x) { return (u16)(pack2(x, 0.f) & 0xffffu); }
; DI int crow(int reg, int h) { return (reg & 3) + 8 * (reg >> 2) + 4 * h; }
; DI void prep_item(const Params& p, int layer, int item, char* smem) {
;     ...
; #pragma unroll
;     for (int g = 0; g < 4; ++g) {
;       float4 g0 = *(const float4*)(gk + 8 * g + 4 * h);
;       float4 g1 = *(const float4*)(gk + 32 + 8 * g + 4 * h);
;       float4 g2 = *(const float4*)(gk + 64 + 8 * g + 4 * h);
;       acc[0][4 * g] *= r2 * g0.x; acc[0][4 * g + 1] *= r2 * g0.y; acc[0][4 * g + 2] *= r2 * g0.z; acc[0][4 * g + 3] *= r2 * g0.w;
;       acc[1][4 * g] *= r2 * g1.x; acc[1][4 * g + 1] *= r2 * g1.y; acc[1][4 * g + 2] *= r2 * g1.z; acc[1][4 * g + 3] *= r2 * g1.w;
;       kpe[4 * g] *= r2 * g2.x; kpe[4 * g + 1] *= r2 * g2.y; kpe[4 * g + 2] *= r2 * g2.z; kpe[4 * g + 3] *= r2 * g2.w;
;     }
; #pragma unroll
;     for (int reg = 0; reg < 8; ++reg) {
;       float x1 = kpe[reg], x2 = kpe[reg + 8];
;       kpe[reg] = x1 * cs[reg] - x2 * sn[reg];
;       kpe[reg + 8] = x2 * cs[reg] + x1 * sn[reg];
;     }
;     u16* ko = KB + ((size_t)(b * 8 + hd) * 4096 + s) * 96;
; #pragma unroll
;     for (int g = 0; g < 4; ++g) {
;       *(uint2*)(ko + 8 * g + 4 * h) = make_uint2(pack2(acc[0][4 * g], acc[0][4 * g + 1]), pack2(acc[0][4 * g + 2], acc[0][4 * g + 3]));
;       *(uint2*)(ko + 32 + 8 * g + 4 * h) = make_uint2(pack2(acc[1][4 * g], acc[1][4 * g + 1]), pack2(acc[1][4 * g + 2], acc[1][4 * g + 3]));
;       *(uint2*)(ko + 64 + 8 * g + 4 * h) = make_uint2(pack2(kpe[4 * g], kpe[4 * g + 1]), pack2(kpe[4 * g + 2], kpe[4 * g + 3]));
;     }
; #pragma unroll
;     for (int nt = 2; nt < 4; ++nt)
; #pragma unroll
;       for (int i = 0; i < 16; ++i) {
;         const int d = (nt - 2) * 32 + crow(i, h);
;         VTB[((size_t)((b * 8 + hd) * 64 + d)) * 4096 + s] = f2bf(acc[nt][i]);
	v_pk_mul_f32 v[8:9], v[40:41], v[8:9] op_sel_hi:[0,1]
	v_pk_mul_f32 v[38:39], v[22:23], v[14:15]
	v_pk_mul_f32 v[14:15], v[42:43], v[40:41] op_sel_hi:[1,0]
	v_pk_mul_f32 v[52:53], v[8:9], v[76:77]
	v_pk_mul_f32 v[32:33], v[48:49], v[14:15]
	v_pk_mul_f32 v[14:15], v[44:45], v[40:41] op_sel_hi:[1,0]
	v_pk_mul_f32 v[8:9], v[40:41], v[10:11] op_sel_hi:[0,1]
	v_pk_mul_f32 v[36:37], v[20:21], v[14:15]
	v_pk_mul_f32 v[14:15], v[162:163], v[40:41] op_sel_hi:[1,0]
	v_pk_mul_f32 v[48:49], v[8:9], v[78:79]
	v_pk_mul_f32 v[44:45], v[14:15], v[72:73]
	v_pk_mul_f32 v[14:15], v[164:165], v[40:41] op_sel_hi:[1,0]
	s_waitcnt vmcnt(1)
	v_pk_mul_f32 v[8:9], v[40:41], v[178:179] op_sel_hi:[0,1]
	v_pk_mul_f32 v[42:43], v[14:15], v[74:75]
	v_pk_mul_f32 v[14:15], v[170:171], v[40:41] op_sel_hi:[1,0]
	v_pk_mul_f32 v[4:5], v[40:41], v[4:5] op_sel_hi:[0,1]
	v_pk_mul_f32 v[24:25], v[24:25], v[14:15]
	v_pk_mul_f32 v[14:15], v[172:173], v[40:41] op_sel_hi:[1,0]
	v_pk_mul_f32 v[4:5], v[4:5], v[70:71]
	v_pk_mul_f32 v[28:29], v[26:27], v[14:15]
	v_pk_mul_f32 v[14:15], v[174:175], v[40:41] op_sel_hi:[1,0]
	v_pk_mul_f32 v[6:7], v[40:41], v[6:7] op_sel_hi:[0,1]
	v_pk_mul_f32 v[22:23], v[132:133], v[14:15]
	v_pk_mul_f32 v[14:15], v[176:177], v[40:41] op_sel_hi:[1,0]
	v_pk_mul_f32 v[6:7], v[6:7], v[68:69]
	v_pk_mul_f32 v[26:27], v[130:131], v[14:15]
	v_pk_mul_f32 v[14:15], v[188:189], v[8:9]
	v_pk_mul_f32 v[8:9], v[40:41], v[180:181] op_sel_hi:[0,1]
	v_pk_mul_f32 v[20:21], v[56:57], v[8:9]
	s_waitcnt vmcnt(0)
	v_pk_mul_f32 v[8:9], v[40:41], v[182:183] op_sel_hi:[0,1]
	v_pk_mul_f32 v[12:13], v[12:13], v[8:9]
	v_pk_mul_f32 v[8:9], v[40:41], v[184:185] op_sel_hi:[0,1]
	v_pk_mul_f32 v[16:17], v[54:55], v[8:9]
	v_pk_mul_f32 v[8:9], v[40:41], v[166:167] op_sel_hi:[0,1]
	v_pk_mul_f32 v[56:57], v[8:9], v[80:81]
	v_pk_mul_f32 v[8:9], v[40:41], v[168:169] op_sel_hi:[0,1]
	v_pk_mul_f32 v[54:55], v[8:9], v[82:83]
	global_load_dwordx4 v[8:11], v154, s[10:11] offset:96
	v_cvt_pk_bf16_f32 v12, v12, v13
	v_cvt_pk_bf16_f32 v13, v16, v17
	v_cvt_pk_bf16_f32 v34, v34, v35
	v_cvt_pk_bf16_f32 v35, v38, v39
	v_cvt_pk_bf16_f32 v32, v32, v33
	v_cvt_pk_bf16_f32 v33, v36, v37
	v_cvt_pk_bf16_f32 v14, v14, v15
	v_cvt_pk_bf16_f32 v15, v20, v21
	s_waitcnt vmcnt(0)
	v_pk_mul_f32 v[8:9], v[40:41], v[8:9] op_sel_hi:[0,1]
	v_pk_mul_f32 v[46:47], v[46:47], v[8:9]
	v_pk_mul_f32 v[8:9], v[40:41], v[10:11] op_sel_hi:[0,1]
	v_pk_mul_f32 v[50:51], v[50:51], v[8:9]
	global_load_dwordx4 v[8:11], v154, s[10:11] offset:224
	s_waitcnt vmcnt(0)
	v_pk_mul_f32 v[8:9], v[40:41], v[8:9] op_sel_hi:[0,1]
	v_pk_mul_f32 v[10:11], v[40:41], v[10:11] op_sel_hi:[0,1]
	v_pk_mul_f32 v[8:9], v[30:31], v[8:9]
	v_pk_mul_f32 v[10:11], v[18:19], v[10:11]
	v_pk_mul_f32 v[18:19], v[116:117], v[56:57]
	v_pk_mul_f32 v[30:31], v[118:119], v[56:57]
	v_pk_fma_f32 v[18:19], v[118:119], v[44:45], v[18:19] neg_lo:[0,0,1] neg_hi:[0,0,1]
	v_pk_fma_f32 v[30:31], v[116:117], v[44:45], v[30:31]
	v_pk_mul_f32 v[44:45], v[120:121], v[54:55]
	v_pk_mul_f32 v[54:55], v[122:123], v[54:55]
	v_pk_fma_f32 v[44:45], v[122:123], v[42:43], v[44:45] neg_lo:[0,0,1] neg_hi:[0,0,1]
	v_pk_fma_f32 v[42:43], v[120:121], v[42:43], v[54:55]
	v_pk_mul_f32 v[54:55], v[124:125], v[4:5]
	v_pk_mul_f32 v[4:5], v[126:127], v[4:5]
	v_pk_fma_f32 v[54:55], v[126:127], v[52:53], v[54:55] neg_lo:[0,0,1] neg_hi:[0,0,1]
	v_pk_fma_f32 v[4:5], v[124:125], v[52:53], v[4:5]
	v_pk_mul_f32 v[52:53], v[150:151], v[6:7]
	v_pk_mul_f32 v[6:7], v[152:153], v[6:7]
	v_pk_fma_f32 v[52:53], v[152:153], v[48:49], v[52:53] neg_lo:[0,0,1] neg_hi:[0,0,1]
	v_pk_fma_f32 v[6:7], v[150:151], v[48:49], v[6:7]
	v_mov_b64_e32 v[48:49], s[18:19]
	v_mad_u64_u32 v[48:49], s[18:19], v98, s13, v[48:49]
	v_cvt_pk_bf16_f32 v8, v8, v9
	v_cvt_pk_bf16_f32 v9, v10, v11
	v_lshl_or_b32 v10, s12, 6, v96
	v_mad_i32_i24 v49, s15, v212, v49
	v_cvt_pk_bf16_f32 v4, v4, v5
	v_cvt_pk_bf16_f32 v5, v6, v7
	v_subrev_u32_e32 v6, 64, v10
	v_readlane_b32 s12, v252, 12
	v_lshl_add_u64 v[48:49], v[48:49], 0, v[2:3]
	v_lshlrev_b32_e32 v2, 1, v97
	v_readlane_b32 s13, v252, 13
	v_ashrrev_i32_e32 v7, 31, v6
	v_cvt_pk_bf16_f32 v18, v18, v19
	v_cvt_pk_bf16_f32 v19, v44, v45
	global_store_dwordx2 v[48:49], v[4:5], off offset:176
	v_lshl_add_u64 v[4:5], s[12:13], 0, v[2:3]
	v_lshlrev_b64 v[6:7], 13, v[6:7]
	global_store_dwordx2 v[48:49], v[18:19], off offset:128
	v_cvt_pk_bf16_f32 v18, v24, v25
	v_cvt_pk_bf16_f32 v19, v28, v29
	v_lshl_add_u64 v[6:7], v[4:5], 0, v[6:7]
	global_store_dwordx2 v[48:49], v[18:19], off offset:16
	v_cvt_pk_bf16_f32 v18, v22, v23
	v_cvt_pk_bf16_f32 v19, v26, v27
	global_store_dwordx2 v[48:49], v[12:13], off offset:96
	v_cvt_pk_bf16_f32 v12, v30, v31
	v_cvt_pk_bf16_f32 v13, v42, v43
	global_store_dwordx2 v[48:49], v[8:9], off offset:112
	v_add_co_u32_e32 v8, vcc, s5, v6
	global_store_dwordx2 v[48:49], v[18:19], off offset:80
	v_cvt_pk_bf16_f32 v18, v54, v55
	v_cvt_pk_bf16_f32 v19, v52, v53
	global_store_dwordx2 v[48:49], v[12:13], off offset:160
	v_cvt_pk_bf16_f32 v12, v46, v47
	v_cvt_pk_bf16_f32 v13, v50, v51
	v_cvt_pk_bf16_f32 v2, v108, s0
	v_addc_co_u32_e32 v9, vcc, 0, v7, vcc
	global_store_dwordx2 v[48:49], v[34:35], off
	global_store_dwordx2 v[48:49], v[32:33], off offset:64
	global_store_dwordx2 v[48:49], v[18:19], off offset:144
	global_store_dwordx2 v[48:49], v[14:15], off offset:32
	global_store_dwordx2 v[48:49], v[12:13], off offset:48
	global_store_short v[8:9], v2, off
	v_or_b32_e32 v8, 1, v10
	v_ashrrev_i32_e32 v9, 31, v8
	v_lshlrev_b64 v[8:9], 13, v[8:9]
	v_cvt_pk_bf16_f32 v2, v107, s0
	v_lshl_add_u64 v[8:9], v[4:5], 0, v[8:9]
	global_store_short v[8:9], v2, off
	v_or_b32_e32 v8, 2, v10
	v_ashrrev_i32_e32 v9, 31, v8
; DI u16 f2bf(float x) { return (u16)(pack2(x, 0.f) & 0xffffu); }
; DI int crow(int reg, int h) { return (reg & 3) + 8 * (reg >> 2) + 4 * h; }
; DI void prep_item(const Params& p, int layer, int item, char* smem) {
;     ...
; #pragma unroll
;     for (int nt = 2; nt < 4; ++nt)
; #pragma unroll
;       for (int i = 0; i < 16; ++i) {
;         const int d = (nt - 2) * 32 + crow(i, h);
;         VTB[((size_t)((b * 8 + hd) * 64 + d)) * 4096 + s] = f2bf(acc[nt][i]);
;       }
;   }
;   __syncthreads();
;   {
;     const u16* qp = prow + O_DSQ + hd * 64 + 32 * h;
;     u16* qo = (u16*)(p.ws + WS_DSQ) + ((size_t)token * 8 + hd) * 64 + 32 * h;
	v_lshlrev_b64 v[8:9], 13, v[8:9]
	v_cvt_pk_bf16_f32 v2, v106, s0
	v_lshl_add_u64 v[8:9], v[4:5], 0, v[8:9]
	global_store_short v[8:9], v2, off
	v_or_b32_e32 v8, 3, v10
	v_ashrrev_i32_e32 v9, 31, v8
	v_lshlrev_b64 v[8:9], 13, v[8:9]
	v_cvt_pk_bf16_f32 v2, v105, s0
	v_lshl_add_u64 v[8:9], v[4:5], 0, v[8:9]
	global_store_short v[8:9], v2, off
	v_or_b32_e32 v8, 8, v10
	v_ashrrev_i32_e32 v9, 31, v8
	v_lshlrev_b64 v[8:9], 13, v[8:9]
	v_cvt_pk_bf16_f32 v2, v104, s0
	v_lshl_add_u64 v[8:9], v[4:5], 0, v[8:9]
	global_store_short v[8:9], v2, off
	v_or_b32_e32 v8, 9, v10
	v_ashrrev_i32_e32 v9, 31, v8
	v_lshlrev_b64 v[8:9], 13, v[8:9]
	v_cvt_pk_bf16_f32 v2, v103, s0
	v_lshl_add_u64 v[8:9], v[4:5], 0, v[8:9]
	global_store_short v[8:9], v2, off
	v_or_b32_e32 v8, 10, v10
	v_ashrrev_i32_e32 v9, 31, v8
	v_lshlrev_b64 v[8:9], 13, v[8:9]
	v_cvt_pk_bf16_f32 v2, v102, s0
	v_lshl_add_u64 v[8:9], v[4:5], 0, v[8:9]
	global_store_short v[8:9], v2, off
	v_or_b32_e32 v8, 11, v10
	v_ashrrev_i32_e32 v9, 31, v8
	v_lshlrev_b64 v[8:9], 13, v[8:9]
	v_cvt_pk_bf16_f32 v2, v101, s0
	v_lshl_add_u64 v[8:9], v[4:5], 0, v[8:9]
	global_store_short v[8:9], v2, off
	v_or_b32_e32 v8, 16, v10
	v_ashrrev_i32_e32 v9, 31, v8
	v_lshlrev_b64 v[8:9], 13, v[8:9]
	v_cvt_pk_bf16_f32 v2, v100, s0
	v_lshl_add_u64 v[8:9], v[4:5], 0, v[8:9]
	global_store_short v[8:9], v2, off
	v_or_b32_e32 v8, 17, v10
	v_ashrrev_i32_e32 v9, 31, v8
	v_lshlrev_b64 v[8:9], 13, v[8:9]
	v_cvt_pk_bf16_f32 v2, v99, s0
	v_lshl_add_u64 v[8:9], v[4:5], 0, v[8:9]
	global_store_short v[8:9], v2, off
	v_or_b32_e32 v8, 18, v10
	v_ashrrev_i32_e32 v9, 31, v8
	v_lshlrev_b64 v[8:9], 13, v[8:9]
	v_cvt_pk_bf16_f32 v2, v95, s0
	v_lshl_add_u64 v[8:9], v[4:5], 0, v[8:9]
	global_store_short v[8:9], v2, off
	v_or_b32_e32 v8, 19, v10
	v_ashrrev_i32_e32 v9, 31, v8
	v_lshlrev_b64 v[8:9], 13, v[8:9]
	v_cvt_pk_bf16_f32 v2, v94, s0
	v_lshl_add_u64 v[8:9], v[4:5], 0, v[8:9]
	global_store_short v[8:9], v2, off
	v_or_b32_e32 v8, 24, v10
	v_ashrrev_i32_e32 v9, 31, v8
	v_lshlrev_b64 v[8:9], 13, v[8:9]
	v_cvt_pk_bf16_f32 v2, v93, s0
	v_lshl_add_u64 v[8:9], v[4:5], 0, v[8:9]
	global_store_short v[8:9], v2, off
	v_or_b32_e32 v8, 25, v10
	v_ashrrev_i32_e32 v9, 31, v8
	v_lshlrev_b64 v[8:9], 13, v[8:9]
	v_cvt_pk_bf16_f32 v2, v92, s0
	v_lshl_add_u64 v[8:9], v[4:5], 0, v[8:9]
	global_store_short v[8:9], v2, off
	v_or_b32_e32 v8, 26, v10
	v_ashrrev_i32_e32 v9, 31, v8
	v_lshlrev_b64 v[8:9], 13, v[8:9]
	v_cvt_pk_bf16_f32 v2, v91, s0
	v_lshl_add_u64 v[8:9], v[4:5], 0, v[8:9]
	global_store_short v[8:9], v2, off
	v_or_b32_e32 v8, 27, v10
	v_ashrrev_i32_e32 v9, 31, v8
	v_lshlrev_b64 v[8:9], 13, v[8:9]
	s_mov_b32 s5, 0xc0000
	v_cvt_pk_bf16_f32 v2, v90, s0
	v_lshl_add_u64 v[8:9], v[4:5], 0, v[8:9]
	v_add_co_u32_e32 v6, vcc, s5, v6
	global_store_short v[8:9], v2, off
	v_cvt_pk_bf16_f32 v2, v89, s0
	v_addc_co_u32_e32 v7, vcc, 0, v7, vcc
	global_store_short v[6:7], v2, off
	v_or_b32_e32 v6, 33, v10
	v_ashrrev_i32_e32 v7, 31, v6
	v_lshlrev_b64 v[6:7], 13, v[6:7]
	v_cvt_pk_bf16_f32 v2, v88, s0
	v_lshl_add_u64 v[6:7], v[4:5], 0, v[6:7]
	global_store_short v[6:7], v2, off
	v_or_b32_e32 v6, 34, v10
	v_ashrrev_i32_e32 v7, 31, v6
	v_lshlrev_b64 v[6:7], 13, v[6:7]
	v_cvt_pk_bf16_f32 v2, v87, s0
	v_lshl_add_u64 v[6:7], v[4:5], 0, v[6:7]
	global_store_short v[6:7], v2, off
	v_or_b32_e32 v6, 35, v10
	v_ashrrev_i32_e32 v7, 31, v6
	v_lshlrev_b64 v[6:7], 13, v[6:7]
	v_cvt_pk_bf16_f32 v2, v86, s0
	v_lshl_add_u64 v[6:7], v[4:5], 0, v[6:7]
	global_store_short v[6:7], v2, off
	v_or_b32_e32 v6, 40, v10
	v_ashrrev_i32_e32 v7, 31, v6
	v_lshlrev_b64 v[6:7], 13, v[6:7]
	v_cvt_pk_bf16_f32 v2, v85, s0
	v_lshl_add_u64 v[6:7], v[4:5], 0, v[6:7]
	global_store_short v[6:7], v2, off
	v_or_b32_e32 v6, 41, v10
	v_ashrrev_i32_e32 v7, 31, v6
	v_lshlrev_b64 v[6:7], 13, v[6:7]
	v_cvt_pk_bf16_f32 v2, v67, s0
	v_lshl_add_u64 v[6:7], v[4:5], 0, v[6:7]
	global_store_short v[6:7], v2, off
	v_or_b32_e32 v6, 42, v10
	v_ashrrev_i32_e32 v7, 31, v6
	v_lshlrev_b64 v[6:7], 13, v[6:7]
	v_cvt_pk_bf16_f32 v2, v66, s0
	v_lshl_add_u64 v[6:7], v[4:5], 0, v[6:7]
	global_store_short v[6:7], v2, off
	v_or_b32_e32 v6, 43, v10
	v_ashrrev_i32_e32 v7, 31, v6
	v_lshlrev_b64 v[6:7], 13, v[6:7]
	v_cvt_pk_bf16_f32 v2, v65, s0
	v_lshl_add_u64 v[6:7], v[4:5], 0, v[6:7]
	global_store_short v[6:7], v2, off
	v_or_b32_e32 v6, 48, v10
	v_ashrrev_i32_e32 v7, 31, v6
	v_lshlrev_b64 v[6:7], 13, v[6:7]
	v_cvt_pk_bf16_f32 v2, v64, s0
	v_lshl_add_u64 v[6:7], v[4:5], 0, v[6:7]
	global_store_short v[6:7], v2, off
	v_or_b32_e32 v6, 49, v10
	v_ashrrev_i32_e32 v7, 31, v6
	v_lshlrev_b64 v[6:7], 13, v[6:7]
	v_cvt_pk_bf16_f32 v2, v63, s0
	v_lshl_add_u64 v[6:7], v[4:5], 0, v[6:7]
	global_store_short v[6:7], v2, off
	v_or_b32_e32 v6, 50, v10
	v_ashrrev_i32_e32 v7, 31, v6
	v_lshlrev_b64 v[6:7], 13, v[6:7]
	v_cvt_pk_bf16_f32 v2, v62, s0
	v_lshl_add_u64 v[6:7], v[4:5], 0, v[6:7]
	global_store_short v[6:7], v2, off
	v_or_b32_e32 v6, 51, v10
	v_ashrrev_i32_e32 v7, 31, v6
	v_lshlrev_b64 v[6:7], 13, v[6:7]
	v_cvt_pk_bf16_f32 v2, v61, s0
	v_lshl_add_u64 v[6:7], v[4:5], 0, v[6:7]
	global_store_short v[6:7], v2, off
	v_or_b32_e32 v6, 56, v10
	v_ashrrev_i32_e32 v7, 31, v6
	v_lshlrev_b64 v[6:7], 13, v[6:7]
	v_cvt_pk_bf16_f32 v2, v60, s0
	v_lshl_add_u64 v[6:7], v[4:5], 0, v[6:7]
	global_store_short v[6:7], v2, off
	v_or_b32_e32 v6, 57, v10
	v_ashrrev_i32_e32 v7, 31, v6
	v_lshlrev_b64 v[6:7], 13, v[6:7]
	v_cvt_pk_bf16_f32 v2, v59, s0
	v_lshl_add_u64 v[6:7], v[4:5], 0, v[6:7]
	global_store_short v[6:7], v2, off
	v_or_b32_e32 v6, 58, v10
	v_ashrrev_i32_e32 v7, 31, v6
	v_lshlrev_b64 v[6:7], 13, v[6:7]
	v_cvt_pk_bf16_f32 v2, v58, s0
	v_lshl_add_u64 v[6:7], v[4:5], 0, v[6:7]
	global_store_short v[6:7], v2, off
	v_or_b32_e32 v6, 59, v10
	v_ashrrev_i32_e32 v7, 31, v6
	v_lshlrev_b64 v[6:7], 13, v[6:7]
	v_cvt_pk_bf16_f32 v2, v41, s0
	v_lshl_add_u64 v[4:5], v[4:5], 0, v[6:7]
	global_store_short v[4:5], v2, off
	v_and_b32_e32 v4, 32, v159
	v_lshl_add_u64 v[6:7], v[114:115], 0, s[16:17]
	v_lshlrev_b32_e32 v2, 1, v4
	v_readlane_b32 s12, v252, 20
	v_lshl_add_u64 v[14:15], v[6:7], 0, v[2:3]
	v_lshlrev_b64 v[6:7], 10, v[0:1]
	v_readlane_b32 s13, v252, 21
	s_barrier
; DI uint32_t pack2(float a, float b) { f2_t v = {a, b}; bf2_t r = __builtin_convertvector(v, bf2_t); return __builtin_bit_cast(uint32_t, r); }
; DI float bflo(uint32_t u) { return __uint_as_float(u << 16); }
; DI float bfhi(uint32_t u) { return __uint_as_float(u & 0xffff0000u); }
; DI float xor32(float v) { return __shfl_xor(v, 32); }
; DI void prep_item(const Params& p, int layer, int item, char* smem) {
;     ...
;   {
;     const u16* qp = prow + O_DSQ + hd * 64 + 32 * h;
;     u16* qo = (u16*)(p.ws + WS_DSQ) + ((size_t)token * 8 + hd) * 64 + 32 * h;
;     uint4 u[4];
;     float f[32];
;     float ss = 0.f;
; #pragma unroll
;     for (int i = 0; i < 4; ++i) {
;       u[i] = *(const uint4*)(qp + 8 * i);
;       f[8 * i] = bflo(u[i].x); f[8 * i + 1] = bfhi(u[i].x); f[8 * i + 2] = bflo(u[i].y); f[8 * i + 3] = bfhi(u[i].y);
;       f[8 * i + 4] = bflo(u[i].z); f[8 * i + 5] = bfhi(u[i].z); f[8 * i + 6] = bflo(u[i].w); f[8 * i + 7] = bfhi(u[i].w);
;     }
; #pragma unroll
;     for (int i = 0; i < 32; ++i) ss += f[i] * f[i];
;     ss += xor32(ss);
;     const float rr = rsqrtf(ss * (1.f / 64.f) + EPS) * C_SB;
;     const float* gq = p.dsa_q_g + layer * 64 + 32 * h;
; #pragma unroll
;     for (int i = 0; i < 4; ++i) {
;       float4 ga = *(const float4*)(gq + 8 * i), gb = *(const float4*)(gq + 8 * i + 4);
;       *(uint4*)(qo + 8 * i) = make_uint4(pack2(f[8 * i] * rr * ga.x, f[8 * i + 1] * rr * ga.y), pack2(f[8 * i + 2] * rr * ga.z, f[8 * i + 3] * rr * ga.w),
;                                          pack2(f[8 * i + 4] * rr * gb.x, f[8 * i + 5] * rr * gb.y), pack2(f[8 * i + 6] * rr * gb.z, f[8 * i + 7] * rr * gb.w));
;     }
;   }
;   if (hd == 1) {
	s_nop 0
	v_lshl_add_u64 v[6:7], s[12:13], 0, v[6:7]
	v_lshl_add_u64 v[44:45], v[6:7], 0, s[16:17]
	global_load_dwordx4 v[40:43], v[14:15], off offset:816
	global_load_dwordx4 v[6:9], v[14:15], off offset:800
	global_load_dwordx4 v[10:13], v[14:15], off offset:784
	s_nop 0
	global_load_dwordx4 v[14:17], v[14:15], off offset:768
	v_lshlrev_b32_e32 v5, 2, v4
	s_mov_b32 s5, 0x800000
	s_mov_b64 s[12:13], -1
	s_waitcnt vmcnt(2)
	v_lshlrev_b32_e32 v22, 16, v6
	s_waitcnt vmcnt(1)
	v_lshlrev_b32_e32 v30, 16, v10
	s_waitcnt vmcnt(0)
	v_lshlrev_b32_e32 v38, 16, v14
	v_and_b32_e32 v39, 0xffff0000, v14
	v_lshlrev_b32_e32 v36, 16, v15
	v_and_b32_e32 v37, 0xffff0000, v15
	v_lshlrev_b32_e32 v34, 16, v16
	v_and_b32_e32 v35, 0xffff0000, v16
	v_lshlrev_b32_e32 v32, 16, v17
	v_and_b32_e32 v33, 0xffff0000, v17
	v_and_b32_e32 v31, 0xffff0000, v10
	v_lshlrev_b32_e32 v28, 16, v11
	v_and_b32_e32 v29, 0xffff0000, v11
	v_lshlrev_b32_e32 v26, 16, v12
	v_and_b32_e32 v27, 0xffff0000, v12
	v_lshlrev_b32_e32 v24, 16, v13
	v_and_b32_e32 v25, 0xffff0000, v13
	v_and_b32_e32 v23, 0xffff0000, v6
	v_lshlrev_b32_e32 v20, 16, v7
	v_and_b32_e32 v21, 0xffff0000, v7
	v_lshlrev_b32_e32 v18, 16, v8
	v_and_b32_e32 v19, 0xffff0000, v8
	v_lshlrev_b32_e32 v16, 16, v9
	v_and_b32_e32 v17, 0xffff0000, v9
	v_lshlrev_b32_e32 v14, 16, v40
	v_and_b32_e32 v15, 0xffff0000, v40
	v_lshlrev_b32_e32 v12, 16, v41
	v_and_b32_e32 v13, 0xffff0000, v41
	v_lshlrev_b32_e32 v11, 16, v42
	v_and_b32_e32 v10, 0xffff0000, v42
	v_lshlrev_b32_e32 v9, 16, v43
	v_and_b32_e32 v8, 0xffff0000, v43
	v_lshl_add_u64 v[6:7], v[44:45], 0, v[2:3]
	global_load_dwordx4 v[40:43], v5, s[6:7] offset:16
	global_load_dwordx4 v[44:47], v5, s[6:7]
	v_pk_mul_f32 v[58:59], v[38:39], v[38:39]
	v_pk_mul_f32 v[56:57], v[36:37], v[36:37]
	v_add_f32_e32 v2, v58, v59
	v_add_f32_e32 v2, v2, v56
	v_pk_mul_f32 v[54:55], v[34:35], v[34:35]
	v_add_f32_e32 v2, v57, v2
	v_add_f32_e32 v2, v54, v2
	v_pk_mul_f32 v[52:53], v[32:33], v[32:33]
	v_add_f32_e32 v2, v55, v2
	v_add_f32_e32 v2, v52, v2
	v_pk_mul_f32 v[66:67], v[30:31], v[30:31]
	v_add_f32_e32 v2, v53, v2
	v_add_f32_e32 v2, v66, v2
	v_pk_mul_f32 v[64:65], v[28:29], v[28:29]
	v_add_f32_e32 v2, v67, v2
	v_add_f32_e32 v2, v64, v2
	v_pk_mul_f32 v[62:63], v[26:27], v[26:27]
	v_add_f32_e32 v2, v65, v2
	v_add_f32_e32 v2, v62, v2
	v_pk_mul_f32 v[60:61], v[24:25], v[24:25]
	v_add_f32_e32 v2, v63, v2
	v_add_f32_e32 v2, v60, v2
	v_pk_mul_f32 v[74:75], v[22:23], v[22:23]
	v_add_f32_e32 v2, v61, v2
	v_add_f32_e32 v2, v74, v2
	v_pk_mul_f32 v[72:73], v[20:21], v[20:21]
	v_add_f32_e32 v2, v75, v2
	v_add_f32_e32 v2, v72, v2
	v_pk_mul_f32 v[70:71], v[18:19], v[18:19]
	v_add_f32_e32 v2, v73, v2
	v_add_f32_e32 v2, v70, v2
	v_pk_mul_f32 v[68:69], v[16:17], v[16:17]
	v_add_f32_e32 v2, v71, v2
	v_add_f32_e32 v2, v68, v2
	v_pk_mul_f32 v[78:79], v[14:15], v[14:15]
	v_add_f32_e32 v2, v69, v2
	v_add_f32_e32 v2, v78, v2
	v_pk_mul_f32 v[76:77], v[12:13], v[12:13]
	v_add_f32_e32 v2, v79, v2
	v_add_f32_e32 v2, v76, v2
	v_pk_mul_f32 v[48:49], v[10:11], v[10:11]
	v_add_f32_e32 v2, v77, v2
	v_add_f32_e32 v2, v49, v2
	v_pk_mul_f32 v[50:51], v[8:9], v[8:9]
	v_add_f32_e32 v2, v48, v2
	v_add_f32_e32 v2, v51, v2
	v_add_f32_e32 v2, v50, v2
	ds_bpermute_b32 v48, v155, v2
	s_waitcnt lgkmcnt(0)
	v_add_f32_e32 v2, v2, v48
	v_fmamk_f32 v2, v2, 0x3c800000, v206
	v_cmp_gt_f32_e32 vcc, s30, v2
	v_mul_f32_e32 v48, 0x4b800000, v2
	s_nop 0
	v_cndmask_b32_e32 v2, v2, v48, vcc
	v_rsq_f32_e32 v2, v2
	s_nop 0
	v_mul_f32_e32 v48, 0x45800000, v2
	v_cndmask_b32_e32 v2, v2, v48, vcc
	v_mul_f32_e32 v2, 0x3e38aa3b, v2
	v_pk_mul_f32 v[38:39], v[2:3], v[38:39] op_sel_hi:[0,1]
	v_pk_mul_f32 v[36:37], v[2:3], v[36:37] op_sel_hi:[0,1]
	v_pk_mul_f32 v[34:35], v[2:3], v[34:35] op_sel_hi:[0,1]
	v_pk_mul_f32 v[32:33], v[2:3], v[32:33] op_sel_hi:[0,1]
	v_pk_mul_f32 v[30:31], v[2:3], v[30:31] op_sel_hi:[0,1]
	v_pk_mul_f32 v[28:29], v[2:3], v[28:29] op_sel_hi:[0,1]
	v_pk_mul_f32 v[26:27], v[2:3], v[26:27] op_sel_hi:[0,1]
	v_pk_mul_f32 v[24:25], v[2:3], v[24:25] op_sel_hi:[0,1]
	v_pk_mul_f32 v[22:23], v[2:3], v[22:23] op_sel_hi:[0,1]
	v_pk_mul_f32 v[20:21], v[2:3], v[20:21] op_sel_hi:[0,1]
	v_pk_mul_f32 v[18:19], v[2:3], v[18:19] op_sel_hi:[0,1]
	v_pk_mul_f32 v[16:17], v[2:3], v[16:17] op_sel_hi:[0,1]
	v_pk_mul_f32 v[14:15], v[2:3], v[14:15] op_sel_hi:[0,1]
	s_waitcnt vmcnt(1)
	v_pk_mul_f32 v[34:35], v[40:41], v[34:35]
	s_waitcnt vmcnt(0)
	v_pk_mul_f32 v[38:39], v[44:45], v[38:39]
	v_pk_mul_f32 v[36:37], v[46:47], v[36:37]
	v_pk_mul_f32 v[32:33], v[42:43], v[32:33]
	v_cvt_pk_bf16_f32 v38, v38, v39
	v_cvt_pk_bf16_f32 v39, v36, v37
	v_cvt_pk_bf16_f32 v40, v34, v35
	v_cvt_pk_bf16_f32 v41, v32, v33
	global_store_dwordx4 v[6:7], v[38:41], off
	global_load_dwordx4 v[32:35], v5, s[6:7] offset:48
	s_nop 0
	global_load_dwordx4 v[36:39], v5, s[6:7] offset:32
	v_pk_mul_f32 v[12:13], v[2:3], v[12:13] op_sel_hi:[0,1]
	v_pk_mul_f32 v[10:11], v[2:3], v[10:11] op_sel_hi:[0,1]
	v_pk_mul_f32 v[8:9], v[2:3], v[8:9] op_sel_hi:[0,1]
	s_waitcnt vmcnt(1)
	v_pk_mul_f32 v[26:27], v[32:33], v[26:27]
	s_waitcnt vmcnt(0)
	v_pk_mul_f32 v[30:31], v[36:37], v[30:31]
	v_pk_mul_f32 v[28:29], v[38:39], v[28:29]
	v_pk_mul_f32 v[24:25], v[34:35], v[24:25]
	v_cvt_pk_bf16_f32 v30, v30, v31
	v_cvt_pk_bf16_f32 v31, v28, v29
	v_cvt_pk_bf16_f32 v32, v26, v27
	v_cvt_pk_bf16_f32 v33, v24, v25
	global_store_dwordx4 v[6:7], v[30:33], off offset:16
	global_load_dwordx4 v[24:27], v5, s[6:7] offset:80
	s_nop 0
	global_load_dwordx4 v[28:31], v5, s[6:7] offset:64
	s_waitcnt vmcnt(1)
	v_pk_mul_f32 v[18:19], v[18:19], v[24:25]
	s_waitcnt vmcnt(0)
	v_pk_mul_f32 v[22:23], v[28:29], v[22:23]
	v_pk_mul_f32 v[20:21], v[30:31], v[20:21]
	v_pk_mul_f32 v[16:17], v[16:17], v[26:27]
	v_cvt_pk_bf16_f32 v22, v22, v23
	v_cvt_pk_bf16_f32 v23, v20, v21
	v_cvt_pk_bf16_f32 v24, v18, v19
	v_cvt_pk_bf16_f32 v25, v16, v17
	global_store_dwordx4 v[6:7], v[22:25], off offset:32
	global_load_dwordx4 v[16:19], v5, s[6:7] offset:112
	s_nop 0
	global_load_dwordx4 v[20:23], v5, s[6:7] offset:96
	s_waitcnt vmcnt(1)
	v_pk_mul_f32 v[10:11], v[10:11], v[16:17] op_sel:[1,0] op_sel_hi:[0,1]
	s_waitcnt vmcnt(0)
	v_pk_mul_f32 v[14:15], v[14:15], v[20:21]
	v_pk_mul_f32 v[12:13], v[12:13], v[22:23]
	v_pk_mul_f32 v[8:9], v[8:9], v[18:19] op_sel:[1,0] op_sel_hi:[0,1]
	v_cvt_pk_bf16_f32 v14, v14, v15
	v_cvt_pk_bf16_f32 v15, v12, v13
	v_cvt_pk_bf16_f32 v16, v10, v11
	v_cvt_pk_bf16_f32 v17, v8, v9
	global_store_dwordx4 v[6:7], v[14:17], off offset:48
	s_cbranch_scc1 .LBB0_355
; DI void prep_item(const Params& p, int layer, int item, char* smem) {
;     ...
;   if (hd == 1) {
;     int pm = p.pos[token];
; #pragma unroll
;     for (int off = 1; off < 32; off <<= 1) { const int o = __shfl_xor(pm, off); pm = pm > o ? pm : o; }
;     if (lane == 0) ((int*)(p.ws + WS_PMAX))[tg] = pm;
;   }
	s_cmp_lg_u32 s1, 1
	s_cbranch_scc1 .LBB0_354
	global_load_dword v2, v[112:113], off
	v_xor_b32_e32 v5, 1, v213
	v_cmp_lt_i32_e32 vcc, v5, v160
	s_nop 1
	v_cndmask_b32_e32 v5, v213, v5, vcc
	v_lshlrev_b32_e32 v5, 2, v5
	s_waitcnt vmcnt(0)
	ds_bpermute_b32 v5, v5, v2
	s_waitcnt lgkmcnt(0)
	v_max_i32_e32 v2, v2, v5
	v_xor_b32_e32 v5, 2, v213
	v_cmp_lt_i32_e32 vcc, v5, v160
	s_nop 1
	v_cndmask_b32_e32 v5, v213, v5, vcc
	v_lshlrev_b32_e32 v5, 2, v5
	ds_bpermute_b32 v5, v5, v2
	s_waitcnt lgkmcnt(0)
	v_max_i32_e32 v2, v2, v5
	v_xor_b32_e32 v5, 4, v213
	v_cmp_lt_i32_e32 vcc, v5, v160
	s_nop 1
	v_cndmask_b32_e32 v5, v213, v5, vcc
	v_lshlrev_b32_e32 v5, 2, v5
	ds_bpermute_b32 v5, v5, v2
	s_waitcnt lgkmcnt(0)
	v_max_i32_e32 v2, v2, v5
	v_xor_b32_e32 v5, 8, v213
	v_cmp_lt_i32_e32 vcc, v5, v160
	s_nop 1
	v_cndmask_b32_e32 v5, v213, v5, vcc
	v_lshlrev_b32_e32 v5, 2, v5
	ds_bpermute_b32 v5, v5, v2
	s_waitcnt lgkmcnt(0)
	v_max_i32_e32 v2, v2, v5
	v_xor_b32_e32 v5, 16, v213
	v_cmp_lt_i32_e32 vcc, v5, v160
	s_nop 1
	v_cndmask_b32_e32 v5, v213, v5, vcc
	v_lshlrev_b32_e32 v5, 2, v5
	ds_bpermute_b32 v5, v5, v2
	v_cmp_eq_u32_e32 vcc, 0, v158
	s_and_saveexec_b64 s[12:13], vcc
	s_cbranch_execz .LBB0_353
	s_ashr_i32 s1, s0, 31
	s_lshl_b64 s[0:1], s[0:1], 2
	v_readlane_b32 s14, v252, 26
	v_readlane_b32 s15, v252, 27
	s_add_u32 s0, s14, s0
	s_addc_u32 s1, s15, s1
	s_waitcnt lgkmcnt(0)
	v_max_i32_e32 v2, v2, v5
	global_store_dword v3, v2, s[0:1]
